# GEMM K-loops: first iteration peeled with SrcC=0, 128-instruction accumulator zero-init removed per tile (on stag2+prio)
# baseline (speedup 1.0000x reference)
.LBB0_237:
	s_or_b64 exec, exec, s[2:3]
	s_ashr_i32 s3, s9, 2
	s_lshr_b32 s2, s30, 3
	s_lshl_b32 s36, s3, 2
	s_ashr_i32 s23, s22, 31
	s_and_b32 s7, s29, 56
	s_and_b32 s31, s2, 3
	s_sub_i32 s8, s8, s36
	s_lshl_b64 s[2:3], s[22:23], 19
	s_add_u32 s2, s16, s2
	s_addc_u32 s3, s17, s3
	s_ashr_i32 s9, s8, 31
	v_mov_b32_e32 v8, v190
	s_lshl_b64 s[22:23], s[8:9], 19
	s_mov_b32 s9, 0x1ffff80
	v_and_b32_e32 v0, 15, v8
	v_lshrrev_b32_e32 v2, 1, v8
	v_and_or_b32 v0, v2, s9, v0
	v_bfe_u32 v1, v8, 4, 2
	v_lshlrev_b32_e32 v132, 7, v0
	v_bfe_u32 v0, v8, 1, 3
	v_bitop3_b32 v0, v1, v0, 4 bitop3:0x36
	v_lshlrev_b32_e32 v133, 4, v0
	v_lshlrev_b32_e32 v0, 7, v8
	v_and_b32_e32 v134, 0x6780, v0
	v_ashrrev_i32_e32 v0, 3, v8
	v_bitop3_b32 v2, v2, v1, 7 bitop3:0x6c
	v_ashrrev_i32_e32 v1, 31, v0
	v_lshrrev_b32_e32 v9, 4, v8
	v_lshlrev_b64 v[0:1], 11, v[0:1]
	s_add_u32 s34, s25, s22
	v_lshlrev_b32_e32 v135, 4, v2
	v_xor_b32_e32 v4, v9, v8
	v_lshl_add_u64 v[2:3], s[2:3], 0, v[0:1]
	v_readfirstlane_b32 s2, v8
	s_addc_u32 s35, s26, s23
	v_lshlrev_b32_e32 v4, 4, v4
	s_lshl_b32 s2, s2, 4
	v_and_b32_e32 v144, 0x70, v4
	s_and_b32 s2, s2, 0xfffffc00
	v_lshl_add_u64 v[2:3], v[2:3], 0, v[144:145]
	s_mov_b32 m0, s2
	s_mov_b64 s[38:39], 0x20000
	v_lshl_add_u64 v[4:5], s[34:35], 0, v[0:1]
	s_waitcnt lgkmcnt(0)
	s_barrier
	global_load_lds_dwordx4 v[2:3], off
	v_lshl_add_u64 v[6:7], v[2:3], 0, s[38:39]
	s_add_i32 m0, s2, 0x2000
	s_mov_b64 s[34:35], 0x40000
	global_load_lds_dwordx4 v[6:7], off
	v_lshl_add_u64 v[6:7], v[2:3], 0, s[34:35]
	s_add_i32 m0, s2, 0x4000
	s_mov_b64 s[40:41], 0x60000
	global_load_lds_dwordx4 v[6:7], off
	v_lshl_add_u64 v[2:3], v[2:3], 0, s[40:41]
	s_add_i32 m0, s2, 0x6000
	v_lshl_add_u64 v[4:5], v[4:5], 0, v[144:145]
	global_load_lds_dwordx4 v[2:3], off
	s_add_i32 m0, s2, 0x8000
	v_lshl_add_u64 v[2:3], v[4:5], 0, s[38:39]
	global_load_lds_dwordx4 v[4:5], off
	s_add_i32 m0, s2, 0xa000
	s_add_i32 s7, s7, s36
	global_load_lds_dwordx4 v[2:3], off
	v_lshl_add_u64 v[2:3], v[4:5], 0, s[34:35]
	s_add_i32 m0, s2, 0xc000
	global_load_lds_dwordx4 v[2:3], off
	v_lshl_add_u64 v[2:3], v[4:5], 0, s[40:41]
	s_add_i32 m0, s2, 0xe000
	v_bitop3_b32 v4, v9, 7, v8 bitop3:0x48
	global_load_lds_dwordx4 v[2:3], off
	v_lshl_add_u64 v[2:3], s[22:23], 0, v[0:1]
	s_or_b32 s22, s7, s31
	s_ashr_i32 s23, s22, 31
	s_lshl_b64 s[22:23], s[22:23], 19
	s_waitcnt vmcnt(0)
	v_lshlrev_b32_e32 v4, 4, v4
	v_lshl_add_u64 v[0:1], s[22:23], 0, v[0:1]
	v_or_b32_e32 v2, v2, v4
	v_or_b32_e32 v0, v0, v4
	s_mov_b64 s[86:87], 0x20000
	v_lshl_add_u64 v[128:129], s[14:15], 0, v[2:3]
	v_lshl_add_u64 v[130:131], s[14:15], 0, v[0:1]
	s_mov_b64 s[22:23], 0
	s_mov_b32 s3, 0
	s_mov_b64 s[36:37], 0x3a20080
	s_mov_b64 s[38:39], 0x3a40080
	s_waitcnt vmcnt(0) lgkmcnt(0)
	s_barrier
	s_bitcmp1_b32 s2, 12
	s_cbranch_scc1 .Lkb_238
	s_add_i32 s7, s3, 0x10000
	s_and_b32 s9, s7, 0x10000
	s_add_i32 s9, s2, s9
	v_lshl_add_u64 v[244:245], v[130:131], 0, s[22:23]
	v_lshl_add_u64 v[246:247], v[244:245], 0, s[44:45]
	s_mov_b32 m0, s9
	s_mov_b64 s[34:35], 0x2100080
	global_load_lds_dwordx4 v[246:247], off
	v_lshl_add_u64 v[246:247], v[244:245], 0, s[46:47]
	s_add_i32 m0, s9, 0x2000
	s_nop 0
	global_load_lds_dwordx4 v[246:247], off
	v_lshl_add_u64 v[246:247], v[244:245], 0, s[36:37]
	s_add_i32 m0, s9, 0x4000
	v_lshl_add_u64 v[244:245], v[244:245], 0, s[38:39]
	global_load_lds_dwordx4 v[246:247], off
	s_add_i32 m0, s9, 0x6000
	s_nop 0
	global_load_lds_dwordx4 v[244:245], off
	v_lshl_add_u64 v[244:245], v[128:129], 0, s[22:23]
	v_lshl_add_u64 v[246:247], v[244:245], 0, s[34:35]
	s_add_i32 m0, s9, 0x8000
	s_mov_b64 s[34:35], 0x2120080
	global_load_lds_dwordx4 v[246:247], off
	v_lshl_add_u64 v[246:247], v[244:245], 0, s[34:35]
	s_add_i32 m0, s9, 0xa000
	s_mov_b64 s[34:35], 0x2140080
	global_load_lds_dwordx4 v[246:247], off
	v_lshl_add_u64 v[246:247], v[244:245], 0, s[34:35]
	s_add_i32 m0, s9, 0xc000
	s_mov_b64 s[34:35], 0x2160080
	global_load_lds_dwordx4 v[246:247], off
	v_lshl_add_u64 v[244:245], v[244:245], 0, s[34:35]
	s_add_i32 m0, s9, 0xe000
	s_nop 0
	global_load_lds_dwordx4 v[244:245], off
	s_and_b32 s3, s3, 0x10000
	v_or_b32_e32 v144, s3, v135
	v_add_u32_e32 v151, v144, v134
	v_add_u32_e32 v144, v144, v132
	ds_read_b128 v[136:139], v151 offset:32768
	ds_read_b128 v[140:143], v151 offset:34816
	ds_read_b128 v[146:149], v151 offset:36864
	ds_read_b128 v[154:157], v151 offset:38912
	ds_read_b128 v[158:161], v144
	ds_read_b128 v[162:165], v144 offset:2048
	ds_read_b128 v[166:169], v144 offset:4096
	ds_read_b128 v[170:173], v144 offset:6144
	ds_read_b128 v[174:177], v144 offset:8192
	ds_read_b128 v[178:181], v144 offset:10240
	ds_read_b128 v[182:185], v144 offset:12288
	ds_read_b128 v[186:189], v144 offset:14336
	s_waitcnt lgkmcnt(0)
	v_mfma_f32_16x16x32_bf16 v[124:127], v[136:139], v[158:161], 0
	v_mfma_f32_16x16x32_bf16 v[120:123], v[140:143], v[158:161], 0
	v_mfma_f32_16x16x32_bf16 v[116:119], v[146:149], v[158:161], 0
	v_mfma_f32_16x16x32_bf16 v[112:115], v[154:157], v[158:161], 0
	v_mfma_f32_16x16x32_bf16 v[108:111], v[136:139], v[162:165], 0
	v_mfma_f32_16x16x32_bf16 v[104:107], v[140:143], v[162:165], 0
	v_mfma_f32_16x16x32_bf16 v[100:103], v[146:149], v[162:165], 0
	v_mfma_f32_16x16x32_bf16 v[96:99], v[154:157], v[162:165], 0
	v_mfma_f32_16x16x32_bf16 v[92:95], v[136:139], v[166:169], 0
	v_mfma_f32_16x16x32_bf16 v[84:87], v[140:143], v[166:169], 0
	v_mfma_f32_16x16x32_bf16 v[80:83], v[146:149], v[166:169], 0
	v_mfma_f32_16x16x32_bf16 v[76:79], v[154:157], v[166:169], 0
	v_mfma_f32_16x16x32_bf16 v[72:75], v[136:139], v[170:173], 0
	v_mfma_f32_16x16x32_bf16 v[68:71], v[140:143], v[170:173], 0
	v_mfma_f32_16x16x32_bf16 v[64:67], v[146:149], v[170:173], 0
	v_mfma_f32_16x16x32_bf16 v[60:63], v[154:157], v[170:173], 0
	v_or_b32_e32 v144, s3, v133
	v_add_u32_e32 v151, v144, v134
	v_add_u32_e32 v144, v144, v132
	ds_read_b128 v[158:161], v151 offset:32768
	ds_read_b128 v[162:165], v151 offset:34816
	ds_read_b128 v[166:169], v151 offset:36864
	ds_read_b128 v[170:173], v151 offset:38912
	ds_read_b128 v[206:209], v144
	ds_read_b128 v[216:219], v144 offset:2048
	ds_read_b128 v[220:223], v144 offset:4096
	ds_read_b128 v[224:227], v144 offset:6144
	v_mfma_f32_16x16x32_bf16 v[56:59], v[136:139], v[174:177], 0
	v_mfma_f32_16x16x32_bf16 v[52:55], v[140:143], v[174:177], 0
	v_mfma_f32_16x16x32_bf16 v[48:51], v[146:149], v[174:177], 0
	v_mfma_f32_16x16x32_bf16 v[44:47], v[154:157], v[174:177], 0
	v_mfma_f32_16x16x32_bf16 v[40:43], v[136:139], v[178:181], 0
	v_mfma_f32_16x16x32_bf16 v[36:39], v[140:143], v[178:181], 0
	v_mfma_f32_16x16x32_bf16 v[32:35], v[146:149], v[178:181], 0
	v_mfma_f32_16x16x32_bf16 v[28:31], v[154:157], v[178:181], 0
	v_mfma_f32_16x16x32_bf16 v[24:27], v[136:139], v[182:185], 0
	v_mfma_f32_16x16x32_bf16 v[20:23], v[140:143], v[182:185], 0
	v_mfma_f32_16x16x32_bf16 v[16:19], v[146:149], v[182:185], 0
	v_mfma_f32_16x16x32_bf16 v[12:15], v[154:157], v[182:185], 0
	v_mfma_f32_16x16x32_bf16 v[8:11], v[136:139], v[186:189], 0
	v_mfma_f32_16x16x32_bf16 v[4:7], v[140:143], v[186:189], 0
	v_mfma_f32_16x16x32_bf16 v[0:3], v[146:149], v[186:189], 0
	v_mfma_f32_16x16x32_bf16 v[88:91], v[154:157], v[186:189], 0
	ds_read_b128 v[136:139], v144 offset:8192
	ds_read_b128 v[140:143], v144 offset:10240
	ds_read_b128 v[146:149], v144 offset:12288
	ds_read_b128 v[154:157], v144 offset:14336
	s_waitcnt lgkmcnt(0)
	v_mfma_f32_16x16x32_bf16 v[124:127], v[158:161], v[206:209], v[124:127]
	v_mfma_f32_16x16x32_bf16 v[120:123], v[162:165], v[206:209], v[120:123]
	v_mfma_f32_16x16x32_bf16 v[116:119], v[166:169], v[206:209], v[116:119]
	v_mfma_f32_16x16x32_bf16 v[112:115], v[170:173], v[206:209], v[112:115]
	v_mfma_f32_16x16x32_bf16 v[108:111], v[158:161], v[216:219], v[108:111]
	v_mfma_f32_16x16x32_bf16 v[104:107], v[162:165], v[216:219], v[104:107]
	v_mfma_f32_16x16x32_bf16 v[100:103], v[166:169], v[216:219], v[100:103]
	v_mfma_f32_16x16x32_bf16 v[96:99], v[170:173], v[216:219], v[96:99]
	v_mfma_f32_16x16x32_bf16 v[92:95], v[158:161], v[220:223], v[92:95]
	v_mfma_f32_16x16x32_bf16 v[84:87], v[162:165], v[220:223], v[84:87]
	v_mfma_f32_16x16x32_bf16 v[80:83], v[166:169], v[220:223], v[80:83]
	v_mfma_f32_16x16x32_bf16 v[76:79], v[170:173], v[220:223], v[76:79]
	v_mfma_f32_16x16x32_bf16 v[72:75], v[158:161], v[224:227], v[72:75]
	v_mfma_f32_16x16x32_bf16 v[68:71], v[162:165], v[224:227], v[68:71]
	v_mfma_f32_16x16x32_bf16 v[64:67], v[166:169], v[224:227], v[64:67]
	v_mfma_f32_16x16x32_bf16 v[60:63], v[170:173], v[224:227], v[60:63]
	v_mfma_f32_16x16x32_bf16 v[56:59], v[158:161], v[136:139], v[56:59]
	s_add_u32 s22, s22, 0x80
	s_addc_u32 s23, s23, 0
	v_mfma_f32_16x16x32_bf16 v[52:55], v[162:165], v[136:139], v[52:55]
	s_cmpk_eq_i32 s22, 0x780
	s_mov_b32 s3, s7
	s_waitcnt vmcnt(0)
	v_mfma_f32_16x16x32_bf16 v[48:51], v[166:169], v[136:139], v[48:51]
	s_barrier
	v_mfma_f32_16x16x32_bf16 v[44:47], v[170:173], v[136:139], v[44:47]
	v_mfma_f32_16x16x32_bf16 v[40:43], v[158:161], v[140:143], v[40:43]
	v_mfma_f32_16x16x32_bf16 v[36:39], v[162:165], v[140:143], v[36:39]
	v_mfma_f32_16x16x32_bf16 v[32:35], v[166:169], v[140:143], v[32:35]
	v_mfma_f32_16x16x32_bf16 v[28:31], v[170:173], v[140:143], v[28:31]
	v_mfma_f32_16x16x32_bf16 v[24:27], v[158:161], v[146:149], v[24:27]
	v_mfma_f32_16x16x32_bf16 v[20:23], v[162:165], v[146:149], v[20:23]
	v_mfma_f32_16x16x32_bf16 v[16:19], v[166:169], v[146:149], v[16:19]
	v_mfma_f32_16x16x32_bf16 v[12:15], v[170:173], v[146:149], v[12:15]
	v_mfma_f32_16x16x32_bf16 v[8:11], v[158:161], v[154:157], v[8:11]
	v_mfma_f32_16x16x32_bf16 v[4:7], v[162:165], v[154:157], v[4:7]
	v_mfma_f32_16x16x32_bf16 v[0:3], v[166:169], v[154:157], v[0:3]
	v_mfma_f32_16x16x32_bf16 v[88:91], v[170:173], v[154:157], v[88:91]
	s_cbranch_scc1 .Lkx_238
.LBB0_238:
	s_add_i32 s7, s3, 0x10000
	s_and_b32 s9, s7, 0x10000
	s_add_i32 s9, s2, s9
	v_lshl_add_u64 v[244:245], v[130:131], 0, s[22:23]
	v_lshl_add_u64 v[246:247], v[244:245], 0, s[44:45]
	s_mov_b32 m0, s9
	s_mov_b64 s[34:35], 0x2100080
	global_load_lds_dwordx4 v[246:247], off
	v_lshl_add_u64 v[246:247], v[244:245], 0, s[46:47]
	s_add_i32 m0, s9, 0x2000
	s_nop 0
	global_load_lds_dwordx4 v[246:247], off
	v_lshl_add_u64 v[246:247], v[244:245], 0, s[36:37]
	s_add_i32 m0, s9, 0x4000
	v_lshl_add_u64 v[244:245], v[244:245], 0, s[38:39]
	global_load_lds_dwordx4 v[246:247], off
	s_add_i32 m0, s9, 0x6000
	s_nop 0
	global_load_lds_dwordx4 v[244:245], off
	v_lshl_add_u64 v[244:245], v[128:129], 0, s[22:23]
	v_lshl_add_u64 v[246:247], v[244:245], 0, s[34:35]
	s_add_i32 m0, s9, 0x8000
	s_mov_b64 s[34:35], 0x2120080
	global_load_lds_dwordx4 v[246:247], off
	v_lshl_add_u64 v[246:247], v[244:245], 0, s[34:35]
	s_add_i32 m0, s9, 0xa000
	s_mov_b64 s[34:35], 0x2140080
	global_load_lds_dwordx4 v[246:247], off
	v_lshl_add_u64 v[246:247], v[244:245], 0, s[34:35]
	s_add_i32 m0, s9, 0xc000
	s_mov_b64 s[34:35], 0x2160080
	global_load_lds_dwordx4 v[246:247], off
	v_lshl_add_u64 v[244:245], v[244:245], 0, s[34:35]
	s_add_i32 m0, s9, 0xe000
	s_nop 0
	global_load_lds_dwordx4 v[244:245], off
	s_and_b32 s3, s3, 0x10000
	v_or_b32_e32 v144, s3, v135
	v_add_u32_e32 v151, v144, v134
	v_add_u32_e32 v144, v144, v132
	ds_read_b128 v[136:139], v151 offset:32768
	ds_read_b128 v[140:143], v151 offset:34816
	ds_read_b128 v[146:149], v151 offset:36864
	ds_read_b128 v[154:157], v151 offset:38912
	ds_read_b128 v[158:161], v144
	ds_read_b128 v[162:165], v144 offset:2048
	ds_read_b128 v[166:169], v144 offset:4096
	ds_read_b128 v[170:173], v144 offset:6144
	ds_read_b128 v[174:177], v144 offset:8192
	ds_read_b128 v[178:181], v144 offset:10240
	ds_read_b128 v[182:185], v144 offset:12288
	ds_read_b128 v[186:189], v144 offset:14336
	s_waitcnt lgkmcnt(0)
	v_mfma_f32_16x16x32_bf16 v[124:127], v[136:139], v[158:161], v[124:127]
	v_mfma_f32_16x16x32_bf16 v[120:123], v[140:143], v[158:161], v[120:123]
	v_mfma_f32_16x16x32_bf16 v[116:119], v[146:149], v[158:161], v[116:119]
	v_mfma_f32_16x16x32_bf16 v[112:115], v[154:157], v[158:161], v[112:115]
	v_mfma_f32_16x16x32_bf16 v[108:111], v[136:139], v[162:165], v[108:111]
	v_mfma_f32_16x16x32_bf16 v[104:107], v[140:143], v[162:165], v[104:107]
	v_mfma_f32_16x16x32_bf16 v[100:103], v[146:149], v[162:165], v[100:103]
	v_mfma_f32_16x16x32_bf16 v[96:99], v[154:157], v[162:165], v[96:99]
	v_mfma_f32_16x16x32_bf16 v[92:95], v[136:139], v[166:169], v[92:95]
	v_mfma_f32_16x16x32_bf16 v[84:87], v[140:143], v[166:169], v[84:87]
	v_mfma_f32_16x16x32_bf16 v[80:83], v[146:149], v[166:169], v[80:83]
	v_mfma_f32_16x16x32_bf16 v[76:79], v[154:157], v[166:169], v[76:79]
	v_mfma_f32_16x16x32_bf16 v[72:75], v[136:139], v[170:173], v[72:75]
	v_mfma_f32_16x16x32_bf16 v[68:71], v[140:143], v[170:173], v[68:71]
	v_mfma_f32_16x16x32_bf16 v[64:67], v[146:149], v[170:173], v[64:67]
	v_mfma_f32_16x16x32_bf16 v[60:63], v[154:157], v[170:173], v[60:63]
	v_or_b32_e32 v144, s3, v133
	v_add_u32_e32 v151, v144, v134
	v_add_u32_e32 v144, v144, v132
	ds_read_b128 v[158:161], v151 offset:32768
	ds_read_b128 v[162:165], v151 offset:34816
	ds_read_b128 v[166:169], v151 offset:36864
	ds_read_b128 v[170:173], v151 offset:38912
	ds_read_b128 v[206:209], v144
	ds_read_b128 v[216:219], v144 offset:2048
	ds_read_b128 v[220:223], v144 offset:4096
	ds_read_b128 v[224:227], v144 offset:6144
	v_mfma_f32_16x16x32_bf16 v[56:59], v[136:139], v[174:177], v[56:59]
	v_mfma_f32_16x16x32_bf16 v[52:55], v[140:143], v[174:177], v[52:55]
	v_mfma_f32_16x16x32_bf16 v[48:51], v[146:149], v[174:177], v[48:51]
	v_mfma_f32_16x16x32_bf16 v[44:47], v[154:157], v[174:177], v[44:47]
	v_mfma_f32_16x16x32_bf16 v[40:43], v[136:139], v[178:181], v[40:43]
	v_mfma_f32_16x16x32_bf16 v[36:39], v[140:143], v[178:181], v[36:39]
	v_mfma_f32_16x16x32_bf16 v[32:35], v[146:149], v[178:181], v[32:35]
	v_mfma_f32_16x16x32_bf16 v[28:31], v[154:157], v[178:181], v[28:31]
	v_mfma_f32_16x16x32_bf16 v[24:27], v[136:139], v[182:185], v[24:27]
	v_mfma_f32_16x16x32_bf16 v[20:23], v[140:143], v[182:185], v[20:23]
	v_mfma_f32_16x16x32_bf16 v[16:19], v[146:149], v[182:185], v[16:19]
	v_mfma_f32_16x16x32_bf16 v[12:15], v[154:157], v[182:185], v[12:15]
	v_mfma_f32_16x16x32_bf16 v[8:11], v[136:139], v[186:189], v[8:11]
	v_mfma_f32_16x16x32_bf16 v[4:7], v[140:143], v[186:189], v[4:7]
	v_mfma_f32_16x16x32_bf16 v[0:3], v[146:149], v[186:189], v[0:3]
	v_mfma_f32_16x16x32_bf16 v[88:91], v[154:157], v[186:189], v[88:91]
	ds_read_b128 v[136:139], v144 offset:8192
	ds_read_b128 v[140:143], v144 offset:10240
	ds_read_b128 v[146:149], v144 offset:12288
	ds_read_b128 v[154:157], v144 offset:14336
	s_waitcnt lgkmcnt(0)
	v_mfma_f32_16x16x32_bf16 v[124:127], v[158:161], v[206:209], v[124:127]
	v_mfma_f32_16x16x32_bf16 v[120:123], v[162:165], v[206:209], v[120:123]
	v_mfma_f32_16x16x32_bf16 v[116:119], v[166:169], v[206:209], v[116:119]
	v_mfma_f32_16x16x32_bf16 v[112:115], v[170:173], v[206:209], v[112:115]
	v_mfma_f32_16x16x32_bf16 v[108:111], v[158:161], v[216:219], v[108:111]
	v_mfma_f32_16x16x32_bf16 v[104:107], v[162:165], v[216:219], v[104:107]
	v_mfma_f32_16x16x32_bf16 v[100:103], v[166:169], v[216:219], v[100:103]
	v_mfma_f32_16x16x32_bf16 v[96:99], v[170:173], v[216:219], v[96:99]
	v_mfma_f32_16x16x32_bf16 v[92:95], v[158:161], v[220:223], v[92:95]
	v_mfma_f32_16x16x32_bf16 v[84:87], v[162:165], v[220:223], v[84:87]
	v_mfma_f32_16x16x32_bf16 v[80:83], v[166:169], v[220:223], v[80:83]
	v_mfma_f32_16x16x32_bf16 v[76:79], v[170:173], v[220:223], v[76:79]
	v_mfma_f32_16x16x32_bf16 v[72:75], v[158:161], v[224:227], v[72:75]
	v_mfma_f32_16x16x32_bf16 v[68:71], v[162:165], v[224:227], v[68:71]
	v_mfma_f32_16x16x32_bf16 v[64:67], v[166:169], v[224:227], v[64:67]
	v_mfma_f32_16x16x32_bf16 v[60:63], v[170:173], v[224:227], v[60:63]
	v_mfma_f32_16x16x32_bf16 v[56:59], v[158:161], v[136:139], v[56:59]
	s_add_u32 s22, s22, 0x80
	s_addc_u32 s23, s23, 0
	v_mfma_f32_16x16x32_bf16 v[52:55], v[162:165], v[136:139], v[52:55]
	s_cmpk_eq_i32 s22, 0x780
	s_mov_b32 s3, s7
	s_waitcnt vmcnt(0)
	v_mfma_f32_16x16x32_bf16 v[48:51], v[166:169], v[136:139], v[48:51]
	s_barrier
	v_mfma_f32_16x16x32_bf16 v[44:47], v[170:173], v[136:139], v[44:47]
	v_mfma_f32_16x16x32_bf16 v[40:43], v[158:161], v[140:143], v[40:43]
	v_mfma_f32_16x16x32_bf16 v[36:39], v[162:165], v[140:143], v[36:39]
	v_mfma_f32_16x16x32_bf16 v[32:35], v[166:169], v[140:143], v[32:35]
	v_mfma_f32_16x16x32_bf16 v[28:31], v[170:173], v[140:143], v[28:31]
	v_mfma_f32_16x16x32_bf16 v[24:27], v[158:161], v[146:149], v[24:27]
	v_mfma_f32_16x16x32_bf16 v[20:23], v[162:165], v[146:149], v[20:23]
	v_mfma_f32_16x16x32_bf16 v[16:19], v[166:169], v[146:149], v[16:19]
	v_mfma_f32_16x16x32_bf16 v[12:15], v[170:173], v[146:149], v[12:15]
	v_mfma_f32_16x16x32_bf16 v[8:11], v[158:161], v[154:157], v[8:11]
	v_mfma_f32_16x16x32_bf16 v[4:7], v[162:165], v[154:157], v[4:7]
	v_mfma_f32_16x16x32_bf16 v[0:3], v[166:169], v[154:157], v[0:3]
	v_mfma_f32_16x16x32_bf16 v[88:91], v[170:173], v[154:157], v[88:91]
	s_cbranch_scc0 .LBB0_238
	s_branch .Lkx_238
.Lkb_238:
	s_add_i32 s7, s3, 0x10000
	s_and_b32 s9, s7, 0x10000
	s_add_i32 s9, s2, s9
	s_and_b32 s3, s3, 0x10000
	v_or_b32_e32 v144, s3, v135
	v_add_u32_e32 v151, v144, v134
	v_add_u32_e32 v144, v144, v132
	ds_read_b128 v[136:139], v151 offset:32768
	ds_read_b128 v[140:143], v151 offset:34816
	ds_read_b128 v[146:149], v151 offset:36864
	ds_read_b128 v[154:157], v151 offset:38912
	ds_read_b128 v[158:161], v144
	ds_read_b128 v[162:165], v144 offset:2048
	ds_read_b128 v[166:169], v144 offset:4096
	ds_read_b128 v[170:173], v144 offset:6144
	ds_read_b128 v[174:177], v144 offset:8192
	ds_read_b128 v[178:181], v144 offset:10240
	ds_read_b128 v[182:185], v144 offset:12288
	ds_read_b128 v[186:189], v144 offset:14336
	s_waitcnt lgkmcnt(0)
	v_mfma_f32_16x16x32_bf16 v[124:127], v[136:139], v[158:161], 0
	v_mfma_f32_16x16x32_bf16 v[120:123], v[140:143], v[158:161], 0
	v_mfma_f32_16x16x32_bf16 v[116:119], v[146:149], v[158:161], 0
	v_mfma_f32_16x16x32_bf16 v[112:115], v[154:157], v[158:161], 0
	v_mfma_f32_16x16x32_bf16 v[108:111], v[136:139], v[162:165], 0
	v_mfma_f32_16x16x32_bf16 v[104:107], v[140:143], v[162:165], 0
	v_mfma_f32_16x16x32_bf16 v[100:103], v[146:149], v[162:165], 0
	v_mfma_f32_16x16x32_bf16 v[96:99], v[154:157], v[162:165], 0
	v_mfma_f32_16x16x32_bf16 v[92:95], v[136:139], v[166:169], 0
	v_mfma_f32_16x16x32_bf16 v[84:87], v[140:143], v[166:169], 0
	v_mfma_f32_16x16x32_bf16 v[80:83], v[146:149], v[166:169], 0
	v_mfma_f32_16x16x32_bf16 v[76:79], v[154:157], v[166:169], 0
	v_mfma_f32_16x16x32_bf16 v[72:75], v[136:139], v[170:173], 0
	v_mfma_f32_16x16x32_bf16 v[68:71], v[140:143], v[170:173], 0
	v_mfma_f32_16x16x32_bf16 v[64:67], v[146:149], v[170:173], 0
	v_mfma_f32_16x16x32_bf16 v[60:63], v[154:157], v[170:173], 0
	v_or_b32_e32 v144, s3, v133
	v_add_u32_e32 v151, v144, v134
	v_add_u32_e32 v144, v144, v132
	ds_read_b128 v[158:161], v151 offset:32768
	ds_read_b128 v[162:165], v151 offset:34816
	ds_read_b128 v[166:169], v151 offset:36864
	ds_read_b128 v[170:173], v151 offset:38912
	ds_read_b128 v[206:209], v144
	ds_read_b128 v[216:219], v144 offset:2048
	ds_read_b128 v[220:223], v144 offset:4096
	ds_read_b128 v[224:227], v144 offset:6144
	v_mfma_f32_16x16x32_bf16 v[56:59], v[136:139], v[174:177], 0
	v_mfma_f32_16x16x32_bf16 v[52:55], v[140:143], v[174:177], 0
	v_mfma_f32_16x16x32_bf16 v[48:51], v[146:149], v[174:177], 0
	v_mfma_f32_16x16x32_bf16 v[44:47], v[154:157], v[174:177], 0
	v_mfma_f32_16x16x32_bf16 v[40:43], v[136:139], v[178:181], 0
	v_mfma_f32_16x16x32_bf16 v[36:39], v[140:143], v[178:181], 0
	v_mfma_f32_16x16x32_bf16 v[32:35], v[146:149], v[178:181], 0
	v_mfma_f32_16x16x32_bf16 v[28:31], v[154:157], v[178:181], 0
	v_mfma_f32_16x16x32_bf16 v[24:27], v[136:139], v[182:185], 0
	v_mfma_f32_16x16x32_bf16 v[20:23], v[140:143], v[182:185], 0
	v_mfma_f32_16x16x32_bf16 v[16:19], v[146:149], v[182:185], 0
	v_mfma_f32_16x16x32_bf16 v[12:15], v[154:157], v[182:185], 0
	v_mfma_f32_16x16x32_bf16 v[8:11], v[136:139], v[186:189], 0
	v_mfma_f32_16x16x32_bf16 v[4:7], v[140:143], v[186:189], 0
	v_mfma_f32_16x16x32_bf16 v[0:3], v[146:149], v[186:189], 0
	v_mfma_f32_16x16x32_bf16 v[88:91], v[154:157], v[186:189], 0
	v_lshl_add_u64 v[244:245], v[130:131], 0, s[22:23]
	v_lshl_add_u64 v[246:247], v[244:245], 0, s[44:45]
	s_mov_b32 m0, s9
	s_mov_b64 s[34:35], 0x2100080
	global_load_lds_dwordx4 v[246:247], off
	v_lshl_add_u64 v[246:247], v[244:245], 0, s[46:47]
	s_add_i32 m0, s9, 0x2000
	s_nop 0
	global_load_lds_dwordx4 v[246:247], off
	v_lshl_add_u64 v[246:247], v[244:245], 0, s[36:37]
	s_add_i32 m0, s9, 0x4000
	v_lshl_add_u64 v[244:245], v[244:245], 0, s[38:39]
	global_load_lds_dwordx4 v[246:247], off
	s_add_i32 m0, s9, 0x6000
	s_nop 0
	global_load_lds_dwordx4 v[244:245], off
	v_lshl_add_u64 v[244:245], v[128:129], 0, s[22:23]
	v_lshl_add_u64 v[246:247], v[244:245], 0, s[34:35]
	s_add_i32 m0, s9, 0x8000
	s_mov_b64 s[34:35], 0x2120080
	global_load_lds_dwordx4 v[246:247], off
	v_lshl_add_u64 v[246:247], v[244:245], 0, s[34:35]
	s_add_i32 m0, s9, 0xa000
	s_mov_b64 s[34:35], 0x2140080
	global_load_lds_dwordx4 v[246:247], off
	v_lshl_add_u64 v[246:247], v[244:245], 0, s[34:35]
	s_add_i32 m0, s9, 0xc000
	s_mov_b64 s[34:35], 0x2160080
	global_load_lds_dwordx4 v[246:247], off
	v_lshl_add_u64 v[244:245], v[244:245], 0, s[34:35]
	s_add_i32 m0, s9, 0xe000
	s_nop 0
	global_load_lds_dwordx4 v[244:245], off
	ds_read_b128 v[136:139], v144 offset:8192
	ds_read_b128 v[140:143], v144 offset:10240
	ds_read_b128 v[146:149], v144 offset:12288
	ds_read_b128 v[154:157], v144 offset:14336
	s_waitcnt lgkmcnt(0)
	v_mfma_f32_16x16x32_bf16 v[124:127], v[158:161], v[206:209], v[124:127]
	v_mfma_f32_16x16x32_bf16 v[120:123], v[162:165], v[206:209], v[120:123]
	v_mfma_f32_16x16x32_bf16 v[116:119], v[166:169], v[206:209], v[116:119]
	v_mfma_f32_16x16x32_bf16 v[112:115], v[170:173], v[206:209], v[112:115]
	v_mfma_f32_16x16x32_bf16 v[108:111], v[158:161], v[216:219], v[108:111]
	v_mfma_f32_16x16x32_bf16 v[104:107], v[162:165], v[216:219], v[104:107]
	v_mfma_f32_16x16x32_bf16 v[100:103], v[166:169], v[216:219], v[100:103]
	v_mfma_f32_16x16x32_bf16 v[96:99], v[170:173], v[216:219], v[96:99]
	v_mfma_f32_16x16x32_bf16 v[92:95], v[158:161], v[220:223], v[92:95]
	v_mfma_f32_16x16x32_bf16 v[84:87], v[162:165], v[220:223], v[84:87]
	v_mfma_f32_16x16x32_bf16 v[80:83], v[166:169], v[220:223], v[80:83]
	v_mfma_f32_16x16x32_bf16 v[76:79], v[170:173], v[220:223], v[76:79]
	v_mfma_f32_16x16x32_bf16 v[72:75], v[158:161], v[224:227], v[72:75]
	v_mfma_f32_16x16x32_bf16 v[68:71], v[162:165], v[224:227], v[68:71]
	v_mfma_f32_16x16x32_bf16 v[64:67], v[166:169], v[224:227], v[64:67]
	v_mfma_f32_16x16x32_bf16 v[60:63], v[170:173], v[224:227], v[60:63]
	v_mfma_f32_16x16x32_bf16 v[56:59], v[158:161], v[136:139], v[56:59]
	s_add_u32 s22, s22, 0x80
	s_addc_u32 s23, s23, 0
	v_mfma_f32_16x16x32_bf16 v[52:55], v[162:165], v[136:139], v[52:55]
	s_cmpk_eq_i32 s22, 0x780
	s_mov_b32 s3, s7
	s_waitcnt vmcnt(0)
	v_mfma_f32_16x16x32_bf16 v[48:51], v[166:169], v[136:139], v[48:51]
	s_barrier
	v_mfma_f32_16x16x32_bf16 v[44:47], v[170:173], v[136:139], v[44:47]
	v_mfma_f32_16x16x32_bf16 v[40:43], v[158:161], v[140:143], v[40:43]
	v_mfma_f32_16x16x32_bf16 v[36:39], v[162:165], v[140:143], v[36:39]
	v_mfma_f32_16x16x32_bf16 v[32:35], v[166:169], v[140:143], v[32:35]
	v_mfma_f32_16x16x32_bf16 v[28:31], v[170:173], v[140:143], v[28:31]
	v_mfma_f32_16x16x32_bf16 v[24:27], v[158:161], v[146:149], v[24:27]
	v_mfma_f32_16x16x32_bf16 v[20:23], v[162:165], v[146:149], v[20:23]
	v_mfma_f32_16x16x32_bf16 v[16:19], v[166:169], v[146:149], v[16:19]
	v_mfma_f32_16x16x32_bf16 v[12:15], v[170:173], v[146:149], v[12:15]
	v_mfma_f32_16x16x32_bf16 v[8:11], v[158:161], v[154:157], v[8:11]
	v_mfma_f32_16x16x32_bf16 v[4:7], v[162:165], v[154:157], v[4:7]
	v_mfma_f32_16x16x32_bf16 v[0:3], v[166:169], v[154:157], v[0:3]
	v_mfma_f32_16x16x32_bf16 v[88:91], v[170:173], v[154:157], v[88:91]
	s_cbranch_scc1 .Lkx_238

.LBB0_245:
	s_ashr_i32 s2, s28, 5
	s_lshr_b32 s3, s2, 30
	s_add_i32 s3, s2, s3
	s_and_b32 s31, s3, -4
	s_sub_i32 s18, s2, s31
	s_lshl_b32 s2, s28, 3
	s_and_b32 s2, s2, 56
	s_bfe_u32 s30, s28, 0x20003
	s_add_i32 s2, s31, s2
	s_or_b32 s22, s2, s30
	s_ashr_i32 s23, s22, 31
	s_and_b32 s29, s27, 56
	s_lshl_b64 s[2:3], s[22:23], 19
	s_add_u32 s2, s6, s2
	s_addc_u32 s3, s7, s3
	s_ashr_i32 s19, s18, 31
	v_mov_b32_e32 v6, v190
	s_lshl_b64 s[24:25], s[18:19], 19
	s_mov_b32 s19, 0x1ffff80
	v_and_b32_e32 v0, 15, v6
	v_lshrrev_b32_e32 v2, 1, v6
	v_and_or_b32 v0, v2, s19, v0
	s_waitcnt lgkmcnt(0)
	v_bfe_u32 v1, v6, 4, 2
	v_lshlrev_b32_e32 v132, 7, v0
	v_bfe_u32 v0, v6, 1, 3
	v_bitop3_b32 v0, v1, v0, 4 bitop3:0x36
	v_lshlrev_b32_e32 v133, 4, v0
	v_lshlrev_b32_e32 v0, 7, v6
	v_and_b32_e32 v134, 0x6780, v0
	v_ashrrev_i32_e32 v0, 3, v6
	v_bitop3_b32 v2, v2, v1, 7 bitop3:0x6c
	v_ashrrev_i32_e32 v1, 31, v0
	v_lshrrev_b32_e32 v7, 4, v6
	v_lshlrev_b64 v[0:1], 11, v[0:1]
	s_add_u32 s24, s0, s24
	v_lshlrev_b32_e32 v135, 4, v2
	v_xor_b32_e32 v4, v7, v6
	v_lshl_add_u64 v[2:3], s[2:3], 0, v[0:1]
	v_readfirstlane_b32 s2, v6
	s_addc_u32 s25, s26, s25
	v_lshlrev_b32_e32 v4, 4, v4
	s_lshl_b32 s2, s2, 4
	v_and_b32_e32 v144, 0x70, v4
	s_and_b32 s2, s2, 0xfffffc00
	v_lshl_add_u64 v[2:3], v[2:3], 0, v[144:145]
	v_lshl_add_u64 v[4:5], s[24:25], 0, v[0:1]
	s_mov_b32 m0, s2
	s_mov_b64 s[34:35], 0x20000
	v_lshl_add_u64 v[128:129], v[4:5], 0, v[144:145]
	s_waitcnt lgkmcnt(0)
	s_barrier
	global_load_lds_dwordx4 v[2:3], off
	v_lshl_add_u64 v[4:5], v[2:3], 0, s[34:35]
	s_add_i32 m0, s2, 0x2000
	s_mov_b64 s[24:25], 0x40000
	global_load_lds_dwordx4 v[4:5], off
	v_lshl_add_u64 v[4:5], v[2:3], 0, s[24:25]
	s_add_i32 m0, s2, 0x4000
	s_mov_b64 s[36:37], 0x60000
	global_load_lds_dwordx4 v[4:5], off
	v_lshl_add_u64 v[2:3], v[2:3], 0, s[36:37]
	s_add_i32 m0, s2, 0x6000
	s_add_i32 s29, s29, s31
	global_load_lds_dwordx4 v[2:3], off
	s_add_i32 m0, s2, 0x8000
	v_lshl_add_u64 v[2:3], v[128:129], 0, s[34:35]
	global_load_lds_dwordx4 v[128:129], off
	s_add_i32 m0, s2, 0xa000
	global_load_lds_dwordx4 v[2:3], off
	v_lshl_add_u64 v[2:3], v[128:129], 0, s[24:25]
	s_add_i32 m0, s2, 0xc000
	s_or_b32 s24, s29, s30
	global_load_lds_dwordx4 v[2:3], off
	v_lshl_add_u64 v[2:3], v[128:129], 0, s[36:37]
	s_add_i32 m0, s2, 0xe000
	s_ashr_i32 s25, s24, 31
	global_load_lds_dwordx4 v[2:3], off
	s_lshl_b64 s[24:25], s[24:25], 19
	s_waitcnt vmcnt(0)
	v_lshl_add_u64 v[0:1], s[24:25], 0, v[0:1]
	v_bitop3_b32 v2, v7, 7, v6 bitop3:0x48
	v_lshl_or_b32 v0, v2, 4, v0
	s_mov_b64 s[86:87], 0x20000
	v_lshl_add_u64 v[130:131], s[6:7], 0, v[0:1]
	s_mov_b64 s[24:25], 0
	s_mov_b32 s3, 0
	s_waitcnt vmcnt(0) lgkmcnt(0)
	s_barrier
	s_bitcmp1_b32 s2, 12
	s_cbranch_scc1 .Lkb_246
	s_add_i32 s19, s3, 0x10000
	s_and_b32 s23, s19, 0x10000
	s_add_i32 s23, s2, s23
	v_lshl_add_u64 v[244:245], v[130:131], 0, s[24:25]
	v_lshl_add_u64 v[246:247], v[244:245], 0, s[10:11]
	s_mov_b32 m0, s23
	s_nop 0
	global_load_lds_dwordx4 v[246:247], off
	v_lshl_add_u64 v[246:247], v[244:245], 0, s[4:5]
	s_add_i32 m0, s23, 0x2000
	s_nop 0
	global_load_lds_dwordx4 v[246:247], off
	v_lshl_add_u64 v[246:247], v[244:245], 0, s[92:93]
	s_add_i32 m0, s23, 0x4000
	v_lshl_add_u64 v[244:245], v[244:245], 0, s[94:95]
	global_load_lds_dwordx4 v[246:247], off
	s_add_i32 m0, s23, 0x6000
	s_nop 0
	global_load_lds_dwordx4 v[244:245], off
	v_lshl_add_u64 v[244:245], v[128:129], 0, s[24:25]
	v_lshl_add_u64 v[246:247], v[244:245], 0, s[10:11]
	s_add_i32 m0, s23, 0x8000
	s_nop 0
	global_load_lds_dwordx4 v[246:247], off
	v_lshl_add_u64 v[246:247], v[244:245], 0, s[4:5]
	s_add_i32 m0, s23, 0xa000
	s_nop 0
	global_load_lds_dwordx4 v[246:247], off
	v_lshl_add_u64 v[246:247], v[244:245], 0, s[92:93]
	s_add_i32 m0, s23, 0xc000
	v_lshl_add_u64 v[244:245], v[244:245], 0, s[94:95]
	global_load_lds_dwordx4 v[246:247], off
	s_add_i32 m0, s23, 0xe000
	s_nop 0
	global_load_lds_dwordx4 v[244:245], off
	s_and_b32 s3, s3, 0x10000
	v_or_b32_e32 v144, s3, v135
	v_add_u32_e32 v151, v144, v134
	v_add_u32_e32 v144, v144, v132
	ds_read_b128 v[136:139], v151 offset:32768
	ds_read_b128 v[140:143], v151 offset:34816
	ds_read_b128 v[146:149], v151 offset:36864
	ds_read_b128 v[154:157], v151 offset:38912
	ds_read_b128 v[158:161], v144
	ds_read_b128 v[162:165], v144 offset:2048
	ds_read_b128 v[166:169], v144 offset:4096
	ds_read_b128 v[170:173], v144 offset:6144
	ds_read_b128 v[174:177], v144 offset:8192
	ds_read_b128 v[178:181], v144 offset:10240
	ds_read_b128 v[182:185], v144 offset:12288
	ds_read_b128 v[186:189], v144 offset:14336
	s_waitcnt lgkmcnt(0)
	v_mfma_f32_16x16x32_bf16 v[124:127], v[136:139], v[158:161], 0
	v_mfma_f32_16x16x32_bf16 v[120:123], v[140:143], v[158:161], 0
	v_mfma_f32_16x16x32_bf16 v[116:119], v[146:149], v[158:161], 0
	v_mfma_f32_16x16x32_bf16 v[112:115], v[154:157], v[158:161], 0
	v_mfma_f32_16x16x32_bf16 v[108:111], v[136:139], v[162:165], 0
	v_mfma_f32_16x16x32_bf16 v[104:107], v[140:143], v[162:165], 0
	v_mfma_f32_16x16x32_bf16 v[100:103], v[146:149], v[162:165], 0
	v_mfma_f32_16x16x32_bf16 v[96:99], v[154:157], v[162:165], 0
	v_mfma_f32_16x16x32_bf16 v[92:95], v[136:139], v[166:169], 0
	v_mfma_f32_16x16x32_bf16 v[84:87], v[140:143], v[166:169], 0
	v_mfma_f32_16x16x32_bf16 v[80:83], v[146:149], v[166:169], 0
	v_mfma_f32_16x16x32_bf16 v[76:79], v[154:157], v[166:169], 0
	v_mfma_f32_16x16x32_bf16 v[72:75], v[136:139], v[170:173], 0
	v_mfma_f32_16x16x32_bf16 v[68:71], v[140:143], v[170:173], 0
	v_mfma_f32_16x16x32_bf16 v[64:67], v[146:149], v[170:173], 0
	v_mfma_f32_16x16x32_bf16 v[60:63], v[154:157], v[170:173], 0
	v_or_b32_e32 v144, s3, v133
	v_add_u32_e32 v151, v144, v134
	v_add_u32_e32 v144, v144, v132
	ds_read_b128 v[158:161], v151 offset:32768
	ds_read_b128 v[162:165], v151 offset:34816
	ds_read_b128 v[166:169], v151 offset:36864
	ds_read_b128 v[170:173], v151 offset:38912
	ds_read_b128 v[206:209], v144
	ds_read_b128 v[216:219], v144 offset:2048
	ds_read_b128 v[220:223], v144 offset:4096
	ds_read_b128 v[224:227], v144 offset:6144
	v_mfma_f32_16x16x32_bf16 v[56:59], v[136:139], v[174:177], 0
	v_mfma_f32_16x16x32_bf16 v[52:55], v[140:143], v[174:177], 0
	v_mfma_f32_16x16x32_bf16 v[48:51], v[146:149], v[174:177], 0
	v_mfma_f32_16x16x32_bf16 v[44:47], v[154:157], v[174:177], 0
	v_mfma_f32_16x16x32_bf16 v[40:43], v[136:139], v[178:181], 0
	v_mfma_f32_16x16x32_bf16 v[36:39], v[140:143], v[178:181], 0
	v_mfma_f32_16x16x32_bf16 v[32:35], v[146:149], v[178:181], 0
	v_mfma_f32_16x16x32_bf16 v[28:31], v[154:157], v[178:181], 0
	v_mfma_f32_16x16x32_bf16 v[24:27], v[136:139], v[182:185], 0
	v_mfma_f32_16x16x32_bf16 v[20:23], v[140:143], v[182:185], 0
	v_mfma_f32_16x16x32_bf16 v[16:19], v[146:149], v[182:185], 0
	v_mfma_f32_16x16x32_bf16 v[12:15], v[154:157], v[182:185], 0
	v_mfma_f32_16x16x32_bf16 v[8:11], v[136:139], v[186:189], 0
	v_mfma_f32_16x16x32_bf16 v[4:7], v[140:143], v[186:189], 0
	v_mfma_f32_16x16x32_bf16 v[0:3], v[146:149], v[186:189], 0
	v_mfma_f32_16x16x32_bf16 v[88:91], v[154:157], v[186:189], 0
	ds_read_b128 v[136:139], v144 offset:8192
	ds_read_b128 v[140:143], v144 offset:10240
	ds_read_b128 v[146:149], v144 offset:12288
	ds_read_b128 v[154:157], v144 offset:14336
	s_waitcnt lgkmcnt(0)
	v_mfma_f32_16x16x32_bf16 v[124:127], v[158:161], v[206:209], v[124:127]
	v_mfma_f32_16x16x32_bf16 v[120:123], v[162:165], v[206:209], v[120:123]
	v_mfma_f32_16x16x32_bf16 v[116:119], v[166:169], v[206:209], v[116:119]
	v_mfma_f32_16x16x32_bf16 v[112:115], v[170:173], v[206:209], v[112:115]
	v_mfma_f32_16x16x32_bf16 v[108:111], v[158:161], v[216:219], v[108:111]
	v_mfma_f32_16x16x32_bf16 v[104:107], v[162:165], v[216:219], v[104:107]
	v_mfma_f32_16x16x32_bf16 v[100:103], v[166:169], v[216:219], v[100:103]
	v_mfma_f32_16x16x32_bf16 v[96:99], v[170:173], v[216:219], v[96:99]
	v_mfma_f32_16x16x32_bf16 v[92:95], v[158:161], v[220:223], v[92:95]
	v_mfma_f32_16x16x32_bf16 v[84:87], v[162:165], v[220:223], v[84:87]
	v_mfma_f32_16x16x32_bf16 v[80:83], v[166:169], v[220:223], v[80:83]
	v_mfma_f32_16x16x32_bf16 v[76:79], v[170:173], v[220:223], v[76:79]
	v_mfma_f32_16x16x32_bf16 v[72:75], v[158:161], v[224:227], v[72:75]
	v_mfma_f32_16x16x32_bf16 v[68:71], v[162:165], v[224:227], v[68:71]
	v_mfma_f32_16x16x32_bf16 v[64:67], v[166:169], v[224:227], v[64:67]
	v_mfma_f32_16x16x32_bf16 v[60:63], v[170:173], v[224:227], v[60:63]
	v_mfma_f32_16x16x32_bf16 v[56:59], v[158:161], v[136:139], v[56:59]
	s_add_u32 s24, s24, 0x80
	s_addc_u32 s25, s25, 0
	v_mfma_f32_16x16x32_bf16 v[52:55], v[162:165], v[136:139], v[52:55]
	s_cmpk_eq_i32 s24, 0x780
	s_mov_b32 s3, s19
	s_waitcnt vmcnt(0)
	v_mfma_f32_16x16x32_bf16 v[48:51], v[166:169], v[136:139], v[48:51]
	s_barrier
	v_mfma_f32_16x16x32_bf16 v[44:47], v[170:173], v[136:139], v[44:47]
	v_mfma_f32_16x16x32_bf16 v[40:43], v[158:161], v[140:143], v[40:43]
	v_mfma_f32_16x16x32_bf16 v[36:39], v[162:165], v[140:143], v[36:39]
	v_mfma_f32_16x16x32_bf16 v[32:35], v[166:169], v[140:143], v[32:35]
	v_mfma_f32_16x16x32_bf16 v[28:31], v[170:173], v[140:143], v[28:31]
	v_mfma_f32_16x16x32_bf16 v[24:27], v[158:161], v[146:149], v[24:27]
	v_mfma_f32_16x16x32_bf16 v[20:23], v[162:165], v[146:149], v[20:23]
	v_mfma_f32_16x16x32_bf16 v[16:19], v[166:169], v[146:149], v[16:19]
	v_mfma_f32_16x16x32_bf16 v[12:15], v[170:173], v[146:149], v[12:15]
	v_mfma_f32_16x16x32_bf16 v[8:11], v[158:161], v[154:157], v[8:11]
	v_mfma_f32_16x16x32_bf16 v[4:7], v[162:165], v[154:157], v[4:7]
	v_mfma_f32_16x16x32_bf16 v[0:3], v[166:169], v[154:157], v[0:3]
	v_mfma_f32_16x16x32_bf16 v[88:91], v[170:173], v[154:157], v[88:91]
	s_cbranch_scc1 .Lkx_246
.LBB0_246:
	s_add_i32 s19, s3, 0x10000
	s_and_b32 s23, s19, 0x10000
	s_add_i32 s23, s2, s23
	v_lshl_add_u64 v[244:245], v[130:131], 0, s[24:25]
	v_lshl_add_u64 v[246:247], v[244:245], 0, s[10:11]
	s_mov_b32 m0, s23
	s_nop 0
	global_load_lds_dwordx4 v[246:247], off
	v_lshl_add_u64 v[246:247], v[244:245], 0, s[4:5]
	s_add_i32 m0, s23, 0x2000
	s_nop 0
	global_load_lds_dwordx4 v[246:247], off
	v_lshl_add_u64 v[246:247], v[244:245], 0, s[92:93]
	s_add_i32 m0, s23, 0x4000
	v_lshl_add_u64 v[244:245], v[244:245], 0, s[94:95]
	global_load_lds_dwordx4 v[246:247], off
	s_add_i32 m0, s23, 0x6000
	s_nop 0
	global_load_lds_dwordx4 v[244:245], off
	v_lshl_add_u64 v[244:245], v[128:129], 0, s[24:25]
	v_lshl_add_u64 v[246:247], v[244:245], 0, s[10:11]
	s_add_i32 m0, s23, 0x8000
	s_nop 0
	global_load_lds_dwordx4 v[246:247], off
	v_lshl_add_u64 v[246:247], v[244:245], 0, s[4:5]
	s_add_i32 m0, s23, 0xa000
	s_nop 0
	global_load_lds_dwordx4 v[246:247], off
	v_lshl_add_u64 v[246:247], v[244:245], 0, s[92:93]
	s_add_i32 m0, s23, 0xc000
	v_lshl_add_u64 v[244:245], v[244:245], 0, s[94:95]
	global_load_lds_dwordx4 v[246:247], off
	s_add_i32 m0, s23, 0xe000
	s_nop 0
	global_load_lds_dwordx4 v[244:245], off
	s_and_b32 s3, s3, 0x10000
	v_or_b32_e32 v144, s3, v135
	v_add_u32_e32 v151, v144, v134
	v_add_u32_e32 v144, v144, v132
	ds_read_b128 v[136:139], v151 offset:32768
	ds_read_b128 v[140:143], v151 offset:34816
	ds_read_b128 v[146:149], v151 offset:36864
	ds_read_b128 v[154:157], v151 offset:38912
	ds_read_b128 v[158:161], v144
	ds_read_b128 v[162:165], v144 offset:2048
	ds_read_b128 v[166:169], v144 offset:4096
	ds_read_b128 v[170:173], v144 offset:6144
	ds_read_b128 v[174:177], v144 offset:8192
	ds_read_b128 v[178:181], v144 offset:10240
	ds_read_b128 v[182:185], v144 offset:12288
	ds_read_b128 v[186:189], v144 offset:14336
	s_waitcnt lgkmcnt(0)
	v_mfma_f32_16x16x32_bf16 v[124:127], v[136:139], v[158:161], v[124:127]
	v_mfma_f32_16x16x32_bf16 v[120:123], v[140:143], v[158:161], v[120:123]
	v_mfma_f32_16x16x32_bf16 v[116:119], v[146:149], v[158:161], v[116:119]
	v_mfma_f32_16x16x32_bf16 v[112:115], v[154:157], v[158:161], v[112:115]
	v_mfma_f32_16x16x32_bf16 v[108:111], v[136:139], v[162:165], v[108:111]
	v_mfma_f32_16x16x32_bf16 v[104:107], v[140:143], v[162:165], v[104:107]
	v_mfma_f32_16x16x32_bf16 v[100:103], v[146:149], v[162:165], v[100:103]
	v_mfma_f32_16x16x32_bf16 v[96:99], v[154:157], v[162:165], v[96:99]
	v_mfma_f32_16x16x32_bf16 v[92:95], v[136:139], v[166:169], v[92:95]
	v_mfma_f32_16x16x32_bf16 v[84:87], v[140:143], v[166:169], v[84:87]
	v_mfma_f32_16x16x32_bf16 v[80:83], v[146:149], v[166:169], v[80:83]
	v_mfma_f32_16x16x32_bf16 v[76:79], v[154:157], v[166:169], v[76:79]
	v_mfma_f32_16x16x32_bf16 v[72:75], v[136:139], v[170:173], v[72:75]
	v_mfma_f32_16x16x32_bf16 v[68:71], v[140:143], v[170:173], v[68:71]
	v_mfma_f32_16x16x32_bf16 v[64:67], v[146:149], v[170:173], v[64:67]
	v_mfma_f32_16x16x32_bf16 v[60:63], v[154:157], v[170:173], v[60:63]
	v_or_b32_e32 v144, s3, v133
	v_add_u32_e32 v151, v144, v134
	v_add_u32_e32 v144, v144, v132
	ds_read_b128 v[158:161], v151 offset:32768
	ds_read_b128 v[162:165], v151 offset:34816
	ds_read_b128 v[166:169], v151 offset:36864
	ds_read_b128 v[170:173], v151 offset:38912
	ds_read_b128 v[206:209], v144
	ds_read_b128 v[216:219], v144 offset:2048
	ds_read_b128 v[220:223], v144 offset:4096
	ds_read_b128 v[224:227], v144 offset:6144
	v_mfma_f32_16x16x32_bf16 v[56:59], v[136:139], v[174:177], v[56:59]
	v_mfma_f32_16x16x32_bf16 v[52:55], v[140:143], v[174:177], v[52:55]
	v_mfma_f32_16x16x32_bf16 v[48:51], v[146:149], v[174:177], v[48:51]
	v_mfma_f32_16x16x32_bf16 v[44:47], v[154:157], v[174:177], v[44:47]
	v_mfma_f32_16x16x32_bf16 v[40:43], v[136:139], v[178:181], v[40:43]
	v_mfma_f32_16x16x32_bf16 v[36:39], v[140:143], v[178:181], v[36:39]
	v_mfma_f32_16x16x32_bf16 v[32:35], v[146:149], v[178:181], v[32:35]
	v_mfma_f32_16x16x32_bf16 v[28:31], v[154:157], v[178:181], v[28:31]
	v_mfma_f32_16x16x32_bf16 v[24:27], v[136:139], v[182:185], v[24:27]
	v_mfma_f32_16x16x32_bf16 v[20:23], v[140:143], v[182:185], v[20:23]
	v_mfma_f32_16x16x32_bf16 v[16:19], v[146:149], v[182:185], v[16:19]
	v_mfma_f32_16x16x32_bf16 v[12:15], v[154:157], v[182:185], v[12:15]
	v_mfma_f32_16x16x32_bf16 v[8:11], v[136:139], v[186:189], v[8:11]
	v_mfma_f32_16x16x32_bf16 v[4:7], v[140:143], v[186:189], v[4:7]
	v_mfma_f32_16x16x32_bf16 v[0:3], v[146:149], v[186:189], v[0:3]
	v_mfma_f32_16x16x32_bf16 v[88:91], v[154:157], v[186:189], v[88:91]
	ds_read_b128 v[136:139], v144 offset:8192
	ds_read_b128 v[140:143], v144 offset:10240
	ds_read_b128 v[146:149], v144 offset:12288
	ds_read_b128 v[154:157], v144 offset:14336
	s_waitcnt lgkmcnt(0)
	v_mfma_f32_16x16x32_bf16 v[124:127], v[158:161], v[206:209], v[124:127]
	v_mfma_f32_16x16x32_bf16 v[120:123], v[162:165], v[206:209], v[120:123]
	v_mfma_f32_16x16x32_bf16 v[116:119], v[166:169], v[206:209], v[116:119]
	v_mfma_f32_16x16x32_bf16 v[112:115], v[170:173], v[206:209], v[112:115]
	v_mfma_f32_16x16x32_bf16 v[108:111], v[158:161], v[216:219], v[108:111]
	v_mfma_f32_16x16x32_bf16 v[104:107], v[162:165], v[216:219], v[104:107]
	v_mfma_f32_16x16x32_bf16 v[100:103], v[166:169], v[216:219], v[100:103]
	v_mfma_f32_16x16x32_bf16 v[96:99], v[170:173], v[216:219], v[96:99]
	v_mfma_f32_16x16x32_bf16 v[92:95], v[158:161], v[220:223], v[92:95]
	v_mfma_f32_16x16x32_bf16 v[84:87], v[162:165], v[220:223], v[84:87]
	v_mfma_f32_16x16x32_bf16 v[80:83], v[166:169], v[220:223], v[80:83]
	v_mfma_f32_16x16x32_bf16 v[76:79], v[170:173], v[220:223], v[76:79]
	v_mfma_f32_16x16x32_bf16 v[72:75], v[158:161], v[224:227], v[72:75]
	v_mfma_f32_16x16x32_bf16 v[68:71], v[162:165], v[224:227], v[68:71]
	v_mfma_f32_16x16x32_bf16 v[64:67], v[166:169], v[224:227], v[64:67]
	v_mfma_f32_16x16x32_bf16 v[60:63], v[170:173], v[224:227], v[60:63]
	v_mfma_f32_16x16x32_bf16 v[56:59], v[158:161], v[136:139], v[56:59]
	s_add_u32 s24, s24, 0x80
	s_addc_u32 s25, s25, 0
	v_mfma_f32_16x16x32_bf16 v[52:55], v[162:165], v[136:139], v[52:55]
	s_cmpk_eq_i32 s24, 0x780
	s_mov_b32 s3, s19
	s_waitcnt vmcnt(0)
	v_mfma_f32_16x16x32_bf16 v[48:51], v[166:169], v[136:139], v[48:51]
	s_barrier
	v_mfma_f32_16x16x32_bf16 v[44:47], v[170:173], v[136:139], v[44:47]
	v_mfma_f32_16x16x32_bf16 v[40:43], v[158:161], v[140:143], v[40:43]
	v_mfma_f32_16x16x32_bf16 v[36:39], v[162:165], v[140:143], v[36:39]
	v_mfma_f32_16x16x32_bf16 v[32:35], v[166:169], v[140:143], v[32:35]
	v_mfma_f32_16x16x32_bf16 v[28:31], v[170:173], v[140:143], v[28:31]
	v_mfma_f32_16x16x32_bf16 v[24:27], v[158:161], v[146:149], v[24:27]
	v_mfma_f32_16x16x32_bf16 v[20:23], v[162:165], v[146:149], v[20:23]
	v_mfma_f32_16x16x32_bf16 v[16:19], v[166:169], v[146:149], v[16:19]
	v_mfma_f32_16x16x32_bf16 v[12:15], v[170:173], v[146:149], v[12:15]
	v_mfma_f32_16x16x32_bf16 v[8:11], v[158:161], v[154:157], v[8:11]
	v_mfma_f32_16x16x32_bf16 v[4:7], v[162:165], v[154:157], v[4:7]
	v_mfma_f32_16x16x32_bf16 v[0:3], v[166:169], v[154:157], v[0:3]
	v_mfma_f32_16x16x32_bf16 v[88:91], v[170:173], v[154:157], v[88:91]
	s_cbranch_scc0 .LBB0_246
	s_branch .Lkx_246
.Lkb_246:
	s_add_i32 s19, s3, 0x10000
	s_and_b32 s23, s19, 0x10000
	s_add_i32 s23, s2, s23
	s_and_b32 s3, s3, 0x10000
	v_or_b32_e32 v144, s3, v135
	v_add_u32_e32 v151, v144, v134
	v_add_u32_e32 v144, v144, v132
	ds_read_b128 v[136:139], v151 offset:32768
	ds_read_b128 v[140:143], v151 offset:34816
	ds_read_b128 v[146:149], v151 offset:36864
	ds_read_b128 v[154:157], v151 offset:38912
	ds_read_b128 v[158:161], v144
	ds_read_b128 v[162:165], v144 offset:2048
	ds_read_b128 v[166:169], v144 offset:4096
	ds_read_b128 v[170:173], v144 offset:6144
	ds_read_b128 v[174:177], v144 offset:8192
	ds_read_b128 v[178:181], v144 offset:10240
	ds_read_b128 v[182:185], v144 offset:12288
	ds_read_b128 v[186:189], v144 offset:14336
	s_waitcnt lgkmcnt(0)
	v_mfma_f32_16x16x32_bf16 v[124:127], v[136:139], v[158:161], 0
	v_mfma_f32_16x16x32_bf16 v[120:123], v[140:143], v[158:161], 0
	v_mfma_f32_16x16x32_bf16 v[116:119], v[146:149], v[158:161], 0
	v_mfma_f32_16x16x32_bf16 v[112:115], v[154:157], v[158:161], 0
	v_mfma_f32_16x16x32_bf16 v[108:111], v[136:139], v[162:165], 0
	v_mfma_f32_16x16x32_bf16 v[104:107], v[140:143], v[162:165], 0
	v_mfma_f32_16x16x32_bf16 v[100:103], v[146:149], v[162:165], 0
	v_mfma_f32_16x16x32_bf16 v[96:99], v[154:157], v[162:165], 0
	v_mfma_f32_16x16x32_bf16 v[92:95], v[136:139], v[166:169], 0
	v_mfma_f32_16x16x32_bf16 v[84:87], v[140:143], v[166:169], 0
	v_mfma_f32_16x16x32_bf16 v[80:83], v[146:149], v[166:169], 0
	v_mfma_f32_16x16x32_bf16 v[76:79], v[154:157], v[166:169], 0
	v_mfma_f32_16x16x32_bf16 v[72:75], v[136:139], v[170:173], 0
	v_mfma_f32_16x16x32_bf16 v[68:71], v[140:143], v[170:173], 0
	v_mfma_f32_16x16x32_bf16 v[64:67], v[146:149], v[170:173], 0
	v_mfma_f32_16x16x32_bf16 v[60:63], v[154:157], v[170:173], 0
	v_or_b32_e32 v144, s3, v133
	v_add_u32_e32 v151, v144, v134
	v_add_u32_e32 v144, v144, v132
	ds_read_b128 v[158:161], v151 offset:32768
	ds_read_b128 v[162:165], v151 offset:34816
	ds_read_b128 v[166:169], v151 offset:36864
	ds_read_b128 v[170:173], v151 offset:38912
	ds_read_b128 v[206:209], v144
	ds_read_b128 v[216:219], v144 offset:2048
	ds_read_b128 v[220:223], v144 offset:4096
	ds_read_b128 v[224:227], v144 offset:6144
	v_mfma_f32_16x16x32_bf16 v[56:59], v[136:139], v[174:177], 0
	v_mfma_f32_16x16x32_bf16 v[52:55], v[140:143], v[174:177], 0
	v_mfma_f32_16x16x32_bf16 v[48:51], v[146:149], v[174:177], 0
	v_mfma_f32_16x16x32_bf16 v[44:47], v[154:157], v[174:177], 0
	v_mfma_f32_16x16x32_bf16 v[40:43], v[136:139], v[178:181], 0
	v_mfma_f32_16x16x32_bf16 v[36:39], v[140:143], v[178:181], 0
	v_mfma_f32_16x16x32_bf16 v[32:35], v[146:149], v[178:181], 0
	v_mfma_f32_16x16x32_bf16 v[28:31], v[154:157], v[178:181], 0
	v_mfma_f32_16x16x32_bf16 v[24:27], v[136:139], v[182:185], 0
	v_mfma_f32_16x16x32_bf16 v[20:23], v[140:143], v[182:185], 0
	v_mfma_f32_16x16x32_bf16 v[16:19], v[146:149], v[182:185], 0
	v_mfma_f32_16x16x32_bf16 v[12:15], v[154:157], v[182:185], 0
	v_mfma_f32_16x16x32_bf16 v[8:11], v[136:139], v[186:189], 0
	v_mfma_f32_16x16x32_bf16 v[4:7], v[140:143], v[186:189], 0
	v_mfma_f32_16x16x32_bf16 v[0:3], v[146:149], v[186:189], 0
	v_mfma_f32_16x16x32_bf16 v[88:91], v[154:157], v[186:189], 0
	v_lshl_add_u64 v[244:245], v[130:131], 0, s[24:25]
	v_lshl_add_u64 v[246:247], v[244:245], 0, s[10:11]
	s_mov_b32 m0, s23
	s_nop 0
	global_load_lds_dwordx4 v[246:247], off
	v_lshl_add_u64 v[246:247], v[244:245], 0, s[4:5]
	s_add_i32 m0, s23, 0x2000
	s_nop 0
	global_load_lds_dwordx4 v[246:247], off
	v_lshl_add_u64 v[246:247], v[244:245], 0, s[92:93]
	s_add_i32 m0, s23, 0x4000
	v_lshl_add_u64 v[244:245], v[244:245], 0, s[94:95]
	global_load_lds_dwordx4 v[246:247], off
	s_add_i32 m0, s23, 0x6000
	s_nop 0
	global_load_lds_dwordx4 v[244:245], off
	v_lshl_add_u64 v[244:245], v[128:129], 0, s[24:25]
	v_lshl_add_u64 v[246:247], v[244:245], 0, s[10:11]
	s_add_i32 m0, s23, 0x8000
	s_nop 0
	global_load_lds_dwordx4 v[246:247], off
	v_lshl_add_u64 v[246:247], v[244:245], 0, s[4:5]
	s_add_i32 m0, s23, 0xa000
	s_nop 0
	global_load_lds_dwordx4 v[246:247], off
	v_lshl_add_u64 v[246:247], v[244:245], 0, s[92:93]
	s_add_i32 m0, s23, 0xc000
	v_lshl_add_u64 v[244:245], v[244:245], 0, s[94:95]
	global_load_lds_dwordx4 v[246:247], off
	s_add_i32 m0, s23, 0xe000
	s_nop 0
	global_load_lds_dwordx4 v[244:245], off
	ds_read_b128 v[136:139], v144 offset:8192
	ds_read_b128 v[140:143], v144 offset:10240
	ds_read_b128 v[146:149], v144 offset:12288
	ds_read_b128 v[154:157], v144 offset:14336
	s_waitcnt lgkmcnt(0)
	v_mfma_f32_16x16x32_bf16 v[124:127], v[158:161], v[206:209], v[124:127]
	v_mfma_f32_16x16x32_bf16 v[120:123], v[162:165], v[206:209], v[120:123]
	v_mfma_f32_16x16x32_bf16 v[116:119], v[166:169], v[206:209], v[116:119]
	v_mfma_f32_16x16x32_bf16 v[112:115], v[170:173], v[206:209], v[112:115]
	v_mfma_f32_16x16x32_bf16 v[108:111], v[158:161], v[216:219], v[108:111]
	v_mfma_f32_16x16x32_bf16 v[104:107], v[162:165], v[216:219], v[104:107]
	v_mfma_f32_16x16x32_bf16 v[100:103], v[166:169], v[216:219], v[100:103]
	v_mfma_f32_16x16x32_bf16 v[96:99], v[170:173], v[216:219], v[96:99]
	v_mfma_f32_16x16x32_bf16 v[92:95], v[158:161], v[220:223], v[92:95]
	v_mfma_f32_16x16x32_bf16 v[84:87], v[162:165], v[220:223], v[84:87]
	v_mfma_f32_16x16x32_bf16 v[80:83], v[166:169], v[220:223], v[80:83]
	v_mfma_f32_16x16x32_bf16 v[76:79], v[170:173], v[220:223], v[76:79]
	v_mfma_f32_16x16x32_bf16 v[72:75], v[158:161], v[224:227], v[72:75]
	v_mfma_f32_16x16x32_bf16 v[68:71], v[162:165], v[224:227], v[68:71]
	v_mfma_f32_16x16x32_bf16 v[64:67], v[166:169], v[224:227], v[64:67]
	v_mfma_f32_16x16x32_bf16 v[60:63], v[170:173], v[224:227], v[60:63]
	v_mfma_f32_16x16x32_bf16 v[56:59], v[158:161], v[136:139], v[56:59]
	s_add_u32 s24, s24, 0x80
	s_addc_u32 s25, s25, 0
	v_mfma_f32_16x16x32_bf16 v[52:55], v[162:165], v[136:139], v[52:55]
	s_cmpk_eq_i32 s24, 0x780
	s_mov_b32 s3, s19
	s_waitcnt vmcnt(0)
	v_mfma_f32_16x16x32_bf16 v[48:51], v[166:169], v[136:139], v[48:51]
	s_barrier
	v_mfma_f32_16x16x32_bf16 v[44:47], v[170:173], v[136:139], v[44:47]
	v_mfma_f32_16x16x32_bf16 v[40:43], v[158:161], v[140:143], v[40:43]
	v_mfma_f32_16x16x32_bf16 v[36:39], v[162:165], v[140:143], v[36:39]
	v_mfma_f32_16x16x32_bf16 v[32:35], v[166:169], v[140:143], v[32:35]
	v_mfma_f32_16x16x32_bf16 v[28:31], v[170:173], v[140:143], v[28:31]
	v_mfma_f32_16x16x32_bf16 v[24:27], v[158:161], v[146:149], v[24:27]
	v_mfma_f32_16x16x32_bf16 v[20:23], v[162:165], v[146:149], v[20:23]
	v_mfma_f32_16x16x32_bf16 v[16:19], v[166:169], v[146:149], v[16:19]
	v_mfma_f32_16x16x32_bf16 v[12:15], v[170:173], v[146:149], v[12:15]
	v_mfma_f32_16x16x32_bf16 v[8:11], v[158:161], v[154:157], v[8:11]
	v_mfma_f32_16x16x32_bf16 v[4:7], v[162:165], v[154:157], v[4:7]
	v_mfma_f32_16x16x32_bf16 v[0:3], v[166:169], v[154:157], v[0:3]
	v_mfma_f32_16x16x32_bf16 v[88:91], v[170:173], v[154:157], v[88:91]
	s_cbranch_scc1 .Lkx_246

.LBB0_419:
	v_and_b32_e32 v5, 15, v3
	v_lshrrev_b32_e32 v6, 1, v3
	s_mov_b32 s3, 0x1ffff80
	s_lshr_b32 s2, s57, 3
	v_and_or_b32 v5, v6, s3, v5
	s_and_b32 s3, s36, 56
	s_and_b32 s2, s2, 3
	s_add_i32 s3, s3, s61
	s_add_i32 s2, s3, s2
	v_and_b32_e32 v4, 3, v4
	v_lshlrev_b32_e32 v136, 7, v5
	v_bfe_u32 v5, v3, 1, 3
	s_ashr_i32 s3, s2, 31
	v_bitop3_b32 v6, v6, v4, 7 bitop3:0x6c
	v_bitop3_b32 v4, v4, v5, 4 bitop3:0x36
	v_lshlrev_b64 v[0:1], 11, v[0:1]
	v_lshlrev_b32_e32 v2, 4, v2
	s_lshl_b64 s[2:3], s[2:3], 19
	v_lshlrev_b32_e32 v137, 4, v4
	v_lshlrev_b32_e32 v3, 7, v3
	s_waitcnt vmcnt(0)
	v_lshl_add_u64 v[4:5], s[26:27], 0, v[0:1]
	v_and_b32_e32 v144, 0x70, v2
	v_lshl_add_u64 v[0:1], s[2:3], 0, v[0:1]
	v_and_b32_e32 v138, 0x6780, v3
	v_lshl_add_u64 v[2:3], v[4:5], 0, v[144:145]
	v_or_b32_e32 v0, v0, v144
	v_lshlrev_b32_e32 v139, 4, v6
	v_lshl_add_u64 v[132:133], s[14:15], 0, v[2:3]
	v_lshl_add_u64 v[134:135], s[14:15], 0, v[0:1]
	s_mov_b64 s[26:27], 0
	s_mov_b32 s2, 0
	s_mov_b64 s[38:39], 0x3a20080
	s_mov_b64 s[40:41], 0x3a40080
	s_waitcnt vmcnt(0) lgkmcnt(0)
	s_barrier
	s_bitcmp1_b32 s0, 12
	s_cbranch_scc1 .Lkb_420
	s_add_i32 s3, s2, 0x10000
	s_and_b32 s7, s3, 0x10000
	s_add_i32 s7, s0, s7
	v_lshl_add_u64 v[244:245], v[134:135], 0, s[26:27]
	v_lshl_add_u64 v[246:247], v[244:245], 0, s[64:65]
	s_mov_b32 m0, s7
	s_mov_b64 s[62:63], 0x1080080
	global_load_lds_dwordx4 v[246:247], off
	v_lshl_add_u64 v[246:247], v[244:245], 0, s[68:69]
	s_add_i32 m0, s7, 0x2000
	s_nop 0
	global_load_lds_dwordx4 v[246:247], off
	v_lshl_add_u64 v[246:247], v[244:245], 0, s[38:39]
	s_add_i32 m0, s7, 0x4000
	v_lshl_add_u64 v[244:245], v[244:245], 0, s[40:41]
	global_load_lds_dwordx4 v[246:247], off
	s_add_i32 m0, s7, 0x6000
	s_nop 0
	global_load_lds_dwordx4 v[244:245], off
	v_lshl_add_u64 v[244:245], v[132:133], 0, s[26:27]
	v_lshl_add_u64 v[246:247], v[244:245], 0, s[62:63]
	s_add_i32 m0, s7, 0x8000
	s_mov_b64 s[62:63], 0x10a0080
	global_load_lds_dwordx4 v[246:247], off
	v_lshl_add_u64 v[246:247], v[244:245], 0, s[62:63]
	s_add_i32 m0, s7, 0xa000
	s_mov_b64 s[62:63], 0x10c0080
	global_load_lds_dwordx4 v[246:247], off
	v_lshl_add_u64 v[246:247], v[244:245], 0, s[62:63]
	s_add_i32 m0, s7, 0xc000
	s_mov_b64 s[62:63], 0x10e0080
	global_load_lds_dwordx4 v[246:247], off
	v_lshl_add_u64 v[244:245], v[244:245], 0, s[62:63]
	s_add_i32 m0, s7, 0xe000
	s_nop 0
	global_load_lds_dwordx4 v[244:245], off
	s_and_b32 s2, s2, 0x10000
	v_or_b32_e32 v129, s2, v139
	v_add_u32_e32 v144, v129, v138
	v_add_u32_e32 v129, v129, v136
	ds_read_b128 v[140:143], v144 offset:32768
	ds_read_b128 v[146:149], v144 offset:34816
	ds_read_b128 v[154:157], v144 offset:36864
	ds_read_b128 v[158:161], v144 offset:38912
	ds_read_b128 v[162:165], v129
	ds_read_b128 v[166:169], v129 offset:2048
	ds_read_b128 v[170:173], v129 offset:4096
	ds_read_b128 v[174:177], v129 offset:6144
	ds_read_b128 v[178:181], v129 offset:8192
	ds_read_b128 v[182:185], v129 offset:10240
	ds_read_b128 v[186:189], v129 offset:12288
	ds_read_b128 v[206:209], v129 offset:14336
	s_waitcnt lgkmcnt(0)
	v_mfma_f32_16x16x32_bf16 v[124:127], v[140:143], v[162:165], 0
	v_mfma_f32_16x16x32_bf16 v[120:123], v[146:149], v[162:165], 0
	v_mfma_f32_16x16x32_bf16 v[116:119], v[154:157], v[162:165], 0
	v_mfma_f32_16x16x32_bf16 v[112:115], v[158:161], v[162:165], 0
	v_mfma_f32_16x16x32_bf16 v[108:111], v[140:143], v[166:169], 0
	v_mfma_f32_16x16x32_bf16 v[104:107], v[146:149], v[166:169], 0
	v_mfma_f32_16x16x32_bf16 v[100:103], v[154:157], v[166:169], 0
	v_mfma_f32_16x16x32_bf16 v[96:99], v[158:161], v[166:169], 0
	v_mfma_f32_16x16x32_bf16 v[92:95], v[140:143], v[170:173], 0
	v_mfma_f32_16x16x32_bf16 v[84:87], v[146:149], v[170:173], 0
	v_mfma_f32_16x16x32_bf16 v[80:83], v[154:157], v[170:173], 0
	v_mfma_f32_16x16x32_bf16 v[76:79], v[158:161], v[170:173], 0
	v_mfma_f32_16x16x32_bf16 v[72:75], v[140:143], v[174:177], 0
	v_mfma_f32_16x16x32_bf16 v[68:71], v[146:149], v[174:177], 0
	v_mfma_f32_16x16x32_bf16 v[64:67], v[154:157], v[174:177], 0
	v_mfma_f32_16x16x32_bf16 v[60:63], v[158:161], v[174:177], 0
	v_or_b32_e32 v129, s2, v137
	v_add_u32_e32 v144, v129, v138
	v_add_u32_e32 v129, v129, v136
	ds_read_b128 v[162:165], v144 offset:32768
	ds_read_b128 v[166:169], v144 offset:34816
	ds_read_b128 v[170:173], v144 offset:36864
	ds_read_b128 v[174:177], v144 offset:38912
	ds_read_b128 v[216:219], v129
	ds_read_b128 v[220:223], v129 offset:2048
	ds_read_b128 v[224:227], v129 offset:4096
	ds_read_b128 v[228:231], v129 offset:6144
	v_mfma_f32_16x16x32_bf16 v[56:59], v[140:143], v[178:181], 0
	v_mfma_f32_16x16x32_bf16 v[52:55], v[146:149], v[178:181], 0
	v_mfma_f32_16x16x32_bf16 v[48:51], v[154:157], v[178:181], 0
	v_mfma_f32_16x16x32_bf16 v[44:47], v[158:161], v[178:181], 0
	v_mfma_f32_16x16x32_bf16 v[40:43], v[140:143], v[182:185], 0
	v_mfma_f32_16x16x32_bf16 v[36:39], v[146:149], v[182:185], 0
	v_mfma_f32_16x16x32_bf16 v[32:35], v[154:157], v[182:185], 0
	v_mfma_f32_16x16x32_bf16 v[28:31], v[158:161], v[182:185], 0
	v_mfma_f32_16x16x32_bf16 v[24:27], v[140:143], v[186:189], 0
	v_mfma_f32_16x16x32_bf16 v[20:23], v[146:149], v[186:189], 0
	v_mfma_f32_16x16x32_bf16 v[16:19], v[154:157], v[186:189], 0
	v_mfma_f32_16x16x32_bf16 v[12:15], v[158:161], v[186:189], 0
	v_mfma_f32_16x16x32_bf16 v[8:11], v[140:143], v[206:209], 0
	v_mfma_f32_16x16x32_bf16 v[4:7], v[146:149], v[206:209], 0
	v_mfma_f32_16x16x32_bf16 v[0:3], v[154:157], v[206:209], 0
	v_mfma_f32_16x16x32_bf16 v[88:91], v[158:161], v[206:209], 0
	ds_read_b128 v[140:143], v129 offset:8192
	ds_read_b128 v[146:149], v129 offset:10240
	ds_read_b128 v[154:157], v129 offset:12288
	ds_read_b128 v[158:161], v129 offset:14336
	s_waitcnt lgkmcnt(0)
	v_mfma_f32_16x16x32_bf16 v[124:127], v[162:165], v[216:219], v[124:127]
	v_mfma_f32_16x16x32_bf16 v[120:123], v[166:169], v[216:219], v[120:123]
	v_mfma_f32_16x16x32_bf16 v[116:119], v[170:173], v[216:219], v[116:119]
	v_mfma_f32_16x16x32_bf16 v[112:115], v[174:177], v[216:219], v[112:115]
	v_mfma_f32_16x16x32_bf16 v[108:111], v[162:165], v[220:223], v[108:111]
	v_mfma_f32_16x16x32_bf16 v[104:107], v[166:169], v[220:223], v[104:107]
	v_mfma_f32_16x16x32_bf16 v[100:103], v[170:173], v[220:223], v[100:103]
	v_mfma_f32_16x16x32_bf16 v[96:99], v[174:177], v[220:223], v[96:99]
	v_mfma_f32_16x16x32_bf16 v[92:95], v[162:165], v[224:227], v[92:95]
	v_mfma_f32_16x16x32_bf16 v[84:87], v[166:169], v[224:227], v[84:87]
	v_mfma_f32_16x16x32_bf16 v[80:83], v[170:173], v[224:227], v[80:83]
	v_mfma_f32_16x16x32_bf16 v[76:79], v[174:177], v[224:227], v[76:79]
	v_mfma_f32_16x16x32_bf16 v[72:75], v[162:165], v[228:231], v[72:75]
	v_mfma_f32_16x16x32_bf16 v[68:71], v[166:169], v[228:231], v[68:71]
	v_mfma_f32_16x16x32_bf16 v[64:67], v[170:173], v[228:231], v[64:67]
	v_mfma_f32_16x16x32_bf16 v[60:63], v[174:177], v[228:231], v[60:63]
	v_mfma_f32_16x16x32_bf16 v[56:59], v[162:165], v[140:143], v[56:59]
	s_add_u32 s26, s26, 0x80
	s_addc_u32 s27, s27, 0
	v_mfma_f32_16x16x32_bf16 v[52:55], v[166:169], v[140:143], v[52:55]
	s_cmpk_eq_i32 s26, 0x780
	s_mov_b32 s2, s3
	s_waitcnt vmcnt(0)
	v_mfma_f32_16x16x32_bf16 v[48:51], v[170:173], v[140:143], v[48:51]
	s_barrier
	v_mfma_f32_16x16x32_bf16 v[44:47], v[174:177], v[140:143], v[44:47]
	v_mfma_f32_16x16x32_bf16 v[40:43], v[162:165], v[146:149], v[40:43]
	v_mfma_f32_16x16x32_bf16 v[36:39], v[166:169], v[146:149], v[36:39]
	v_mfma_f32_16x16x32_bf16 v[32:35], v[170:173], v[146:149], v[32:35]
	v_mfma_f32_16x16x32_bf16 v[28:31], v[174:177], v[146:149], v[28:31]
	v_mfma_f32_16x16x32_bf16 v[24:27], v[162:165], v[154:157], v[24:27]
	v_mfma_f32_16x16x32_bf16 v[20:23], v[166:169], v[154:157], v[20:23]
	v_mfma_f32_16x16x32_bf16 v[16:19], v[170:173], v[154:157], v[16:19]
	v_mfma_f32_16x16x32_bf16 v[12:15], v[174:177], v[154:157], v[12:15]
	v_mfma_f32_16x16x32_bf16 v[8:11], v[162:165], v[158:161], v[8:11]
	v_mfma_f32_16x16x32_bf16 v[4:7], v[166:169], v[158:161], v[4:7]
	v_mfma_f32_16x16x32_bf16 v[0:3], v[170:173], v[158:161], v[0:3]
	v_mfma_f32_16x16x32_bf16 v[88:91], v[174:177], v[158:161], v[88:91]
	s_cbranch_scc1 .Lkx_420
.LBB0_420:
	s_add_i32 s3, s2, 0x10000
	s_and_b32 s7, s3, 0x10000
	s_add_i32 s7, s0, s7
	v_lshl_add_u64 v[244:245], v[134:135], 0, s[26:27]
	v_lshl_add_u64 v[246:247], v[244:245], 0, s[64:65]
	s_mov_b32 m0, s7
	s_mov_b64 s[62:63], 0x1080080
	global_load_lds_dwordx4 v[246:247], off
	v_lshl_add_u64 v[246:247], v[244:245], 0, s[68:69]
	s_add_i32 m0, s7, 0x2000
	s_nop 0
	global_load_lds_dwordx4 v[246:247], off
	v_lshl_add_u64 v[246:247], v[244:245], 0, s[38:39]
	s_add_i32 m0, s7, 0x4000
	v_lshl_add_u64 v[244:245], v[244:245], 0, s[40:41]
	global_load_lds_dwordx4 v[246:247], off
	s_add_i32 m0, s7, 0x6000
	s_nop 0
	global_load_lds_dwordx4 v[244:245], off
	v_lshl_add_u64 v[244:245], v[132:133], 0, s[26:27]
	v_lshl_add_u64 v[246:247], v[244:245], 0, s[62:63]
	s_add_i32 m0, s7, 0x8000
	s_mov_b64 s[62:63], 0x10a0080
	global_load_lds_dwordx4 v[246:247], off
	v_lshl_add_u64 v[246:247], v[244:245], 0, s[62:63]
	s_add_i32 m0, s7, 0xa000
	s_mov_b64 s[62:63], 0x10c0080
	global_load_lds_dwordx4 v[246:247], off
	v_lshl_add_u64 v[246:247], v[244:245], 0, s[62:63]
	s_add_i32 m0, s7, 0xc000
	s_mov_b64 s[62:63], 0x10e0080
	global_load_lds_dwordx4 v[246:247], off
	v_lshl_add_u64 v[244:245], v[244:245], 0, s[62:63]
	s_add_i32 m0, s7, 0xe000
	s_nop 0
	global_load_lds_dwordx4 v[244:245], off
	s_and_b32 s2, s2, 0x10000
	v_or_b32_e32 v129, s2, v139
	v_add_u32_e32 v144, v129, v138
	v_add_u32_e32 v129, v129, v136
	ds_read_b128 v[140:143], v144 offset:32768
	ds_read_b128 v[146:149], v144 offset:34816
	ds_read_b128 v[154:157], v144 offset:36864
	ds_read_b128 v[158:161], v144 offset:38912
	ds_read_b128 v[162:165], v129
	ds_read_b128 v[166:169], v129 offset:2048
	ds_read_b128 v[170:173], v129 offset:4096
	ds_read_b128 v[174:177], v129 offset:6144
	ds_read_b128 v[178:181], v129 offset:8192
	ds_read_b128 v[182:185], v129 offset:10240
	ds_read_b128 v[186:189], v129 offset:12288
	ds_read_b128 v[206:209], v129 offset:14336
	s_waitcnt lgkmcnt(0)
	v_mfma_f32_16x16x32_bf16 v[124:127], v[140:143], v[162:165], v[124:127]
	v_mfma_f32_16x16x32_bf16 v[120:123], v[146:149], v[162:165], v[120:123]
	v_mfma_f32_16x16x32_bf16 v[116:119], v[154:157], v[162:165], v[116:119]
	v_mfma_f32_16x16x32_bf16 v[112:115], v[158:161], v[162:165], v[112:115]
	v_mfma_f32_16x16x32_bf16 v[108:111], v[140:143], v[166:169], v[108:111]
	v_mfma_f32_16x16x32_bf16 v[104:107], v[146:149], v[166:169], v[104:107]
	v_mfma_f32_16x16x32_bf16 v[100:103], v[154:157], v[166:169], v[100:103]
	v_mfma_f32_16x16x32_bf16 v[96:99], v[158:161], v[166:169], v[96:99]
	v_mfma_f32_16x16x32_bf16 v[92:95], v[140:143], v[170:173], v[92:95]
	v_mfma_f32_16x16x32_bf16 v[84:87], v[146:149], v[170:173], v[84:87]
	v_mfma_f32_16x16x32_bf16 v[80:83], v[154:157], v[170:173], v[80:83]
	v_mfma_f32_16x16x32_bf16 v[76:79], v[158:161], v[170:173], v[76:79]
	v_mfma_f32_16x16x32_bf16 v[72:75], v[140:143], v[174:177], v[72:75]
	v_mfma_f32_16x16x32_bf16 v[68:71], v[146:149], v[174:177], v[68:71]
	v_mfma_f32_16x16x32_bf16 v[64:67], v[154:157], v[174:177], v[64:67]
	v_mfma_f32_16x16x32_bf16 v[60:63], v[158:161], v[174:177], v[60:63]
	v_or_b32_e32 v129, s2, v137
	v_add_u32_e32 v144, v129, v138
	v_add_u32_e32 v129, v129, v136
	ds_read_b128 v[162:165], v144 offset:32768
	ds_read_b128 v[166:169], v144 offset:34816
	ds_read_b128 v[170:173], v144 offset:36864
	ds_read_b128 v[174:177], v144 offset:38912
	ds_read_b128 v[216:219], v129
	ds_read_b128 v[220:223], v129 offset:2048
	ds_read_b128 v[224:227], v129 offset:4096
	ds_read_b128 v[228:231], v129 offset:6144
	v_mfma_f32_16x16x32_bf16 v[56:59], v[140:143], v[178:181], v[56:59]
	v_mfma_f32_16x16x32_bf16 v[52:55], v[146:149], v[178:181], v[52:55]
	v_mfma_f32_16x16x32_bf16 v[48:51], v[154:157], v[178:181], v[48:51]
	v_mfma_f32_16x16x32_bf16 v[44:47], v[158:161], v[178:181], v[44:47]
	v_mfma_f32_16x16x32_bf16 v[40:43], v[140:143], v[182:185], v[40:43]
	v_mfma_f32_16x16x32_bf16 v[36:39], v[146:149], v[182:185], v[36:39]
	v_mfma_f32_16x16x32_bf16 v[32:35], v[154:157], v[182:185], v[32:35]
	v_mfma_f32_16x16x32_bf16 v[28:31], v[158:161], v[182:185], v[28:31]
	v_mfma_f32_16x16x32_bf16 v[24:27], v[140:143], v[186:189], v[24:27]
	v_mfma_f32_16x16x32_bf16 v[20:23], v[146:149], v[186:189], v[20:23]
	v_mfma_f32_16x16x32_bf16 v[16:19], v[154:157], v[186:189], v[16:19]
	v_mfma_f32_16x16x32_bf16 v[12:15], v[158:161], v[186:189], v[12:15]
	v_mfma_f32_16x16x32_bf16 v[8:11], v[140:143], v[206:209], v[8:11]
	v_mfma_f32_16x16x32_bf16 v[4:7], v[146:149], v[206:209], v[4:7]
	v_mfma_f32_16x16x32_bf16 v[0:3], v[154:157], v[206:209], v[0:3]
	v_mfma_f32_16x16x32_bf16 v[88:91], v[158:161], v[206:209], v[88:91]
	ds_read_b128 v[140:143], v129 offset:8192
	ds_read_b128 v[146:149], v129 offset:10240
	ds_read_b128 v[154:157], v129 offset:12288
	ds_read_b128 v[158:161], v129 offset:14336
	s_waitcnt lgkmcnt(0)
	v_mfma_f32_16x16x32_bf16 v[124:127], v[162:165], v[216:219], v[124:127]
	v_mfma_f32_16x16x32_bf16 v[120:123], v[166:169], v[216:219], v[120:123]
	v_mfma_f32_16x16x32_bf16 v[116:119], v[170:173], v[216:219], v[116:119]
	v_mfma_f32_16x16x32_bf16 v[112:115], v[174:177], v[216:219], v[112:115]
	v_mfma_f32_16x16x32_bf16 v[108:111], v[162:165], v[220:223], v[108:111]
	v_mfma_f32_16x16x32_bf16 v[104:107], v[166:169], v[220:223], v[104:107]
	v_mfma_f32_16x16x32_bf16 v[100:103], v[170:173], v[220:223], v[100:103]
	v_mfma_f32_16x16x32_bf16 v[96:99], v[174:177], v[220:223], v[96:99]
	v_mfma_f32_16x16x32_bf16 v[92:95], v[162:165], v[224:227], v[92:95]
	v_mfma_f32_16x16x32_bf16 v[84:87], v[166:169], v[224:227], v[84:87]
	v_mfma_f32_16x16x32_bf16 v[80:83], v[170:173], v[224:227], v[80:83]
	v_mfma_f32_16x16x32_bf16 v[76:79], v[174:177], v[224:227], v[76:79]
	v_mfma_f32_16x16x32_bf16 v[72:75], v[162:165], v[228:231], v[72:75]
	v_mfma_f32_16x16x32_bf16 v[68:71], v[166:169], v[228:231], v[68:71]
	v_mfma_f32_16x16x32_bf16 v[64:67], v[170:173], v[228:231], v[64:67]
	v_mfma_f32_16x16x32_bf16 v[60:63], v[174:177], v[228:231], v[60:63]
	v_mfma_f32_16x16x32_bf16 v[56:59], v[162:165], v[140:143], v[56:59]
	s_add_u32 s26, s26, 0x80
	s_addc_u32 s27, s27, 0
	v_mfma_f32_16x16x32_bf16 v[52:55], v[166:169], v[140:143], v[52:55]
	s_cmpk_eq_i32 s26, 0x780
	s_mov_b32 s2, s3
	s_waitcnt vmcnt(0)
	v_mfma_f32_16x16x32_bf16 v[48:51], v[170:173], v[140:143], v[48:51]
	s_barrier
	v_mfma_f32_16x16x32_bf16 v[44:47], v[174:177], v[140:143], v[44:47]
	v_mfma_f32_16x16x32_bf16 v[40:43], v[162:165], v[146:149], v[40:43]
	v_mfma_f32_16x16x32_bf16 v[36:39], v[166:169], v[146:149], v[36:39]
	v_mfma_f32_16x16x32_bf16 v[32:35], v[170:173], v[146:149], v[32:35]
	v_mfma_f32_16x16x32_bf16 v[28:31], v[174:177], v[146:149], v[28:31]
	v_mfma_f32_16x16x32_bf16 v[24:27], v[162:165], v[154:157], v[24:27]
	v_mfma_f32_16x16x32_bf16 v[20:23], v[166:169], v[154:157], v[20:23]
	v_mfma_f32_16x16x32_bf16 v[16:19], v[170:173], v[154:157], v[16:19]
	v_mfma_f32_16x16x32_bf16 v[12:15], v[174:177], v[154:157], v[12:15]
	v_mfma_f32_16x16x32_bf16 v[8:11], v[162:165], v[158:161], v[8:11]
	v_mfma_f32_16x16x32_bf16 v[4:7], v[166:169], v[158:161], v[4:7]
	v_mfma_f32_16x16x32_bf16 v[0:3], v[170:173], v[158:161], v[0:3]
	v_mfma_f32_16x16x32_bf16 v[88:91], v[174:177], v[158:161], v[88:91]
	s_cbranch_scc0 .LBB0_420
	s_branch .Lkx_420
.Lkb_420:
	s_add_i32 s3, s2, 0x10000
	s_and_b32 s7, s3, 0x10000
	s_add_i32 s7, s0, s7
	s_and_b32 s2, s2, 0x10000
	v_or_b32_e32 v129, s2, v139
	v_add_u32_e32 v144, v129, v138
	v_add_u32_e32 v129, v129, v136
	ds_read_b128 v[140:143], v144 offset:32768
	ds_read_b128 v[146:149], v144 offset:34816
	ds_read_b128 v[154:157], v144 offset:36864
	ds_read_b128 v[158:161], v144 offset:38912
	ds_read_b128 v[162:165], v129
	ds_read_b128 v[166:169], v129 offset:2048
	ds_read_b128 v[170:173], v129 offset:4096
	ds_read_b128 v[174:177], v129 offset:6144
	ds_read_b128 v[178:181], v129 offset:8192
	ds_read_b128 v[182:185], v129 offset:10240
	ds_read_b128 v[186:189], v129 offset:12288
	ds_read_b128 v[206:209], v129 offset:14336
	s_waitcnt lgkmcnt(0)
	v_mfma_f32_16x16x32_bf16 v[124:127], v[140:143], v[162:165], 0
	v_mfma_f32_16x16x32_bf16 v[120:123], v[146:149], v[162:165], 0
	v_mfma_f32_16x16x32_bf16 v[116:119], v[154:157], v[162:165], 0
	v_mfma_f32_16x16x32_bf16 v[112:115], v[158:161], v[162:165], 0
	v_mfma_f32_16x16x32_bf16 v[108:111], v[140:143], v[166:169], 0
	v_mfma_f32_16x16x32_bf16 v[104:107], v[146:149], v[166:169], 0
	v_mfma_f32_16x16x32_bf16 v[100:103], v[154:157], v[166:169], 0
	v_mfma_f32_16x16x32_bf16 v[96:99], v[158:161], v[166:169], 0
	v_mfma_f32_16x16x32_bf16 v[92:95], v[140:143], v[170:173], 0
	v_mfma_f32_16x16x32_bf16 v[84:87], v[146:149], v[170:173], 0
	v_mfma_f32_16x16x32_bf16 v[80:83], v[154:157], v[170:173], 0
	v_mfma_f32_16x16x32_bf16 v[76:79], v[158:161], v[170:173], 0
	v_mfma_f32_16x16x32_bf16 v[72:75], v[140:143], v[174:177], 0
	v_mfma_f32_16x16x32_bf16 v[68:71], v[146:149], v[174:177], 0
	v_mfma_f32_16x16x32_bf16 v[64:67], v[154:157], v[174:177], 0
	v_mfma_f32_16x16x32_bf16 v[60:63], v[158:161], v[174:177], 0
	v_or_b32_e32 v129, s2, v137
	v_add_u32_e32 v144, v129, v138
	v_add_u32_e32 v129, v129, v136
	ds_read_b128 v[162:165], v144 offset:32768
	ds_read_b128 v[166:169], v144 offset:34816
	ds_read_b128 v[170:173], v144 offset:36864
	ds_read_b128 v[174:177], v144 offset:38912
	ds_read_b128 v[216:219], v129
	ds_read_b128 v[220:223], v129 offset:2048
	ds_read_b128 v[224:227], v129 offset:4096
	ds_read_b128 v[228:231], v129 offset:6144
	v_mfma_f32_16x16x32_bf16 v[56:59], v[140:143], v[178:181], 0
	v_mfma_f32_16x16x32_bf16 v[52:55], v[146:149], v[178:181], 0
	v_mfma_f32_16x16x32_bf16 v[48:51], v[154:157], v[178:181], 0
	v_mfma_f32_16x16x32_bf16 v[44:47], v[158:161], v[178:181], 0
	v_mfma_f32_16x16x32_bf16 v[40:43], v[140:143], v[182:185], 0
	v_mfma_f32_16x16x32_bf16 v[36:39], v[146:149], v[182:185], 0
	v_mfma_f32_16x16x32_bf16 v[32:35], v[154:157], v[182:185], 0
	v_mfma_f32_16x16x32_bf16 v[28:31], v[158:161], v[182:185], 0
	v_mfma_f32_16x16x32_bf16 v[24:27], v[140:143], v[186:189], 0
	v_mfma_f32_16x16x32_bf16 v[20:23], v[146:149], v[186:189], 0
	v_mfma_f32_16x16x32_bf16 v[16:19], v[154:157], v[186:189], 0
	v_mfma_f32_16x16x32_bf16 v[12:15], v[158:161], v[186:189], 0
	v_mfma_f32_16x16x32_bf16 v[8:11], v[140:143], v[206:209], 0
	v_mfma_f32_16x16x32_bf16 v[4:7], v[146:149], v[206:209], 0
	v_mfma_f32_16x16x32_bf16 v[0:3], v[154:157], v[206:209], 0
	v_mfma_f32_16x16x32_bf16 v[88:91], v[158:161], v[206:209], 0
	v_lshl_add_u64 v[244:245], v[134:135], 0, s[26:27]
	v_lshl_add_u64 v[246:247], v[244:245], 0, s[64:65]
	s_mov_b32 m0, s7
	s_mov_b64 s[62:63], 0x1080080
	global_load_lds_dwordx4 v[246:247], off
	v_lshl_add_u64 v[246:247], v[244:245], 0, s[68:69]
	s_add_i32 m0, s7, 0x2000
	s_nop 0
	global_load_lds_dwordx4 v[246:247], off
	v_lshl_add_u64 v[246:247], v[244:245], 0, s[38:39]
	s_add_i32 m0, s7, 0x4000
	v_lshl_add_u64 v[244:245], v[244:245], 0, s[40:41]
	global_load_lds_dwordx4 v[246:247], off
	s_add_i32 m0, s7, 0x6000
	s_nop 0
	global_load_lds_dwordx4 v[244:245], off
	v_lshl_add_u64 v[244:245], v[132:133], 0, s[26:27]
	v_lshl_add_u64 v[246:247], v[244:245], 0, s[62:63]
	s_add_i32 m0, s7, 0x8000
	s_mov_b64 s[62:63], 0x10a0080
	global_load_lds_dwordx4 v[246:247], off
	v_lshl_add_u64 v[246:247], v[244:245], 0, s[62:63]
	s_add_i32 m0, s7, 0xa000
	s_mov_b64 s[62:63], 0x10c0080
	global_load_lds_dwordx4 v[246:247], off
	v_lshl_add_u64 v[246:247], v[244:245], 0, s[62:63]
	s_add_i32 m0, s7, 0xc000
	s_mov_b64 s[62:63], 0x10e0080
	global_load_lds_dwordx4 v[246:247], off
	v_lshl_add_u64 v[244:245], v[244:245], 0, s[62:63]
	s_add_i32 m0, s7, 0xe000
	s_nop 0
	global_load_lds_dwordx4 v[244:245], off
	ds_read_b128 v[140:143], v129 offset:8192
	ds_read_b128 v[146:149], v129 offset:10240
	ds_read_b128 v[154:157], v129 offset:12288
	ds_read_b128 v[158:161], v129 offset:14336
	s_waitcnt lgkmcnt(0)
	v_mfma_f32_16x16x32_bf16 v[124:127], v[162:165], v[216:219], v[124:127]
	v_mfma_f32_16x16x32_bf16 v[120:123], v[166:169], v[216:219], v[120:123]
	v_mfma_f32_16x16x32_bf16 v[116:119], v[170:173], v[216:219], v[116:119]
	v_mfma_f32_16x16x32_bf16 v[112:115], v[174:177], v[216:219], v[112:115]
	v_mfma_f32_16x16x32_bf16 v[108:111], v[162:165], v[220:223], v[108:111]
	v_mfma_f32_16x16x32_bf16 v[104:107], v[166:169], v[220:223], v[104:107]
	v_mfma_f32_16x16x32_bf16 v[100:103], v[170:173], v[220:223], v[100:103]
	v_mfma_f32_16x16x32_bf16 v[96:99], v[174:177], v[220:223], v[96:99]
	v_mfma_f32_16x16x32_bf16 v[92:95], v[162:165], v[224:227], v[92:95]
	v_mfma_f32_16x16x32_bf16 v[84:87], v[166:169], v[224:227], v[84:87]
	v_mfma_f32_16x16x32_bf16 v[80:83], v[170:173], v[224:227], v[80:83]
	v_mfma_f32_16x16x32_bf16 v[76:79], v[174:177], v[224:227], v[76:79]
	v_mfma_f32_16x16x32_bf16 v[72:75], v[162:165], v[228:231], v[72:75]
	v_mfma_f32_16x16x32_bf16 v[68:71], v[166:169], v[228:231], v[68:71]
	v_mfma_f32_16x16x32_bf16 v[64:67], v[170:173], v[228:231], v[64:67]
	v_mfma_f32_16x16x32_bf16 v[60:63], v[174:177], v[228:231], v[60:63]
	v_mfma_f32_16x16x32_bf16 v[56:59], v[162:165], v[140:143], v[56:59]
	s_add_u32 s26, s26, 0x80
	s_addc_u32 s27, s27, 0
	v_mfma_f32_16x16x32_bf16 v[52:55], v[166:169], v[140:143], v[52:55]
	s_cmpk_eq_i32 s26, 0x780
	s_mov_b32 s2, s3
	s_waitcnt vmcnt(0)
	v_mfma_f32_16x16x32_bf16 v[48:51], v[170:173], v[140:143], v[48:51]
	s_barrier
	v_mfma_f32_16x16x32_bf16 v[44:47], v[174:177], v[140:143], v[44:47]
	v_mfma_f32_16x16x32_bf16 v[40:43], v[162:165], v[146:149], v[40:43]
	v_mfma_f32_16x16x32_bf16 v[36:39], v[166:169], v[146:149], v[36:39]
	v_mfma_f32_16x16x32_bf16 v[32:35], v[170:173], v[146:149], v[32:35]
	v_mfma_f32_16x16x32_bf16 v[28:31], v[174:177], v[146:149], v[28:31]
	v_mfma_f32_16x16x32_bf16 v[24:27], v[162:165], v[154:157], v[24:27]
	v_mfma_f32_16x16x32_bf16 v[20:23], v[166:169], v[154:157], v[20:23]
	v_mfma_f32_16x16x32_bf16 v[16:19], v[170:173], v[154:157], v[16:19]
	v_mfma_f32_16x16x32_bf16 v[12:15], v[174:177], v[154:157], v[12:15]
	v_mfma_f32_16x16x32_bf16 v[8:11], v[162:165], v[158:161], v[8:11]
	v_mfma_f32_16x16x32_bf16 v[4:7], v[166:169], v[158:161], v[4:7]
	v_mfma_f32_16x16x32_bf16 v[0:3], v[170:173], v[158:161], v[0:3]
	v_mfma_f32_16x16x32_bf16 v[88:91], v[174:177], v[158:161], v[88:91]
	s_cbranch_scc1 .Lkx_420

.LBB0_499:
	s_ashr_i32 s2, s34, 5
	s_lshr_b32 s3, s2, 30
	s_add_i32 s3, s2, s3
	s_and_b32 s36, s3, -4
	s_sub_i32 s35, s2, s36
	s_lshl_b32 s2, s34, 3
	s_and_b32 s2, s2, 56
	s_bfe_u32 s27, s34, 0x20003
	s_add_i32 s2, s36, s2
	s_or_b32 s2, s2, s27
	s_and_b32 s26, s31, 56
	s_mul_i32 s6, s2, 0x160000
	s_mul_hi_i32 s3, s2, 0x160000
	s_add_u32 s6, s29, s6
	s_addc_u32 s7, s30, s3
	s_mul_i32 s3, s35, 0x160000
	s_ashr_i32 s9, s3, 31
	s_waitcnt vmcnt(0) lgkmcnt(0)
	v_mov_b32_e32 v4, v190
	s_add_u32 s8, s0, s3
	s_mov_b32 s3, 0x1ffff80
	v_and_b32_e32 v0, 15, v4
	v_lshrrev_b32_e32 v2, 1, v4
	v_and_or_b32 v0, v2, s3, v0
	v_bfe_u32 v1, v4, 4, 2
	v_lshlrev_b32_e32 v132, 7, v0
	v_bfe_u32 v0, v4, 1, 3
	v_lshrrev_b32_e32 v5, 4, v4
	v_bitop3_b32 v2, v2, v1, 7 bitop3:0x6c
	v_bitop3_b32 v0, v1, v0, 4 bitop3:0x36
	v_lshlrev_b32_e32 v135, 4, v2
	v_lshlrev_b32_e32 v133, 4, v0
	v_lshlrev_b32_e32 v0, 7, v4
	v_xor_b32_e32 v2, v5, v4
	v_readfirstlane_b32 s3, v4
	s_addc_u32 s9, s28, s9
	v_and_b32_e32 v134, 0x6780, v0
	v_ashrrev_i32_e32 v6, 3, v4
	v_mov_b64_e32 v[0:1], s[6:7]
	v_lshlrev_b32_e32 v2, 4, v2
	s_lshl_b32 s3, s3, 4
	v_mad_i64_i32 v[0:1], s[6:7], v6, s33, v[0:1]
	v_and_b32_e32 v144, 0x70, v2
	v_mov_b64_e32 v[2:3], s[8:9]
	s_and_b32 s3, s3, 0xfffffc00
	v_lshl_add_u64 v[0:1], v[0:1], 0, v[144:145]
	v_mad_i64_i32 v[2:3], s[6:7], v6, s33, v[2:3]
	s_mov_b32 m0, s3
	v_lshl_add_u64 v[128:129], v[2:3], 0, v[144:145]
	s_barrier
	global_load_lds_dwordx4 v[0:1], off
	v_lshl_add_u64 v[2:3], v[0:1], 0, s[54:55]
	s_add_i32 m0, s3, 0x2000
	s_add_i32 s26, s26, s36
	global_load_lds_dwordx4 v[2:3], off
	v_lshl_add_u64 v[2:3], v[0:1], 0, s[56:57]
	s_add_i32 m0, s3, 0x4000
	v_lshl_add_u64 v[0:1], v[0:1], 0, s[62:63]
	global_load_lds_dwordx4 v[2:3], off
	s_add_i32 m0, s3, 0x6000
	s_or_b32 s8, s26, s27
	global_load_lds_dwordx4 v[0:1], off
	s_add_i32 m0, s3, 0x8000
	v_lshl_add_u64 v[0:1], v[128:129], 0, s[54:55]
	global_load_lds_dwordx4 v[128:129], off
	s_add_i32 m0, s3, 0xa000
	v_bitop3_b32 v2, v5, 7, v4 bitop3:0x48
	global_load_lds_dwordx4 v[0:1], off
	v_lshl_add_u64 v[0:1], v[128:129], 0, s[56:57]
	s_add_i32 m0, s3, 0xc000
	global_load_lds_dwordx4 v[0:1], off
	v_lshl_add_u64 v[0:1], v[128:129], 0, s[62:63]
	s_add_i32 m0, s3, 0xe000
	global_load_lds_dwordx4 v[0:1], off
	v_mad_i64_i32 v[0:1], s[6:7], v6, s33, 0
	s_waitcnt vmcnt(0)
	v_mad_i64_i32 v[0:1], s[6:7], s8, v210, v[0:1]
	v_lshl_or_b32 v0, v2, 4, v0
	v_lshl_add_u64 v[130:131], s[14:15], 0, v[0:1]
	s_mov_b64 s[6:7], 0
	s_mov_b32 s8, 0
	s_waitcnt vmcnt(0) lgkmcnt(0)
	s_barrier
	s_bitcmp1_b32 s3, 12
	s_cbranch_scc1 .Lkb_500
	s_add_i32 s9, s8, 0x10000
	s_and_b32 s26, s9, 0x10000
	s_add_i32 s36, s3, s26
	v_lshl_add_u64 v[244:245], v[130:131], 0, s[6:7]
	s_mov_b64 s[26:27], 0x59e0080
	v_lshl_add_u64 v[246:247], v[244:245], 0, s[26:27]
	s_mov_b32 m0, s36
	s_mov_b64 s[26:27], 0x5a38080
	global_load_lds_dwordx4 v[246:247], off
	v_lshl_add_u64 v[246:247], v[244:245], 0, s[26:27]
	s_add_i32 m0, s36, 0x2000
	s_mov_b64 s[26:27], 0x5a90080
	global_load_lds_dwordx4 v[246:247], off
	v_lshl_add_u64 v[246:247], v[244:245], 0, s[26:27]
	s_add_i32 m0, s36, 0x4000
	s_mov_b64 s[26:27], 0x5ae8080
	global_load_lds_dwordx4 v[246:247], off
	v_lshl_add_u64 v[244:245], v[244:245], 0, s[26:27]
	s_add_i32 m0, s36, 0x6000
	s_mov_b64 s[26:27], 0x58080
	global_load_lds_dwordx4 v[244:245], off
	v_lshl_add_u64 v[244:245], v[128:129], 0, s[6:7]
	v_lshl_add_u64 v[246:247], v[244:245], 0, s[10:11]
	s_add_i32 m0, s36, 0x8000
	s_nop 0
	global_load_lds_dwordx4 v[246:247], off
	v_lshl_add_u64 v[246:247], v[244:245], 0, s[26:27]
	s_add_i32 m0, s36, 0xa000
	s_mov_b64 s[26:27], 0xb0080
	global_load_lds_dwordx4 v[246:247], off
	v_lshl_add_u64 v[246:247], v[244:245], 0, s[26:27]
	s_add_i32 m0, s36, 0xc000
	s_mov_b64 s[26:27], 0x108080
	global_load_lds_dwordx4 v[246:247], off
	v_lshl_add_u64 v[244:245], v[244:245], 0, s[26:27]
	s_add_i32 m0, s36, 0xe000
	s_nop 0
	global_load_lds_dwordx4 v[244:245], off
	s_and_b32 s8, s8, 0x10000
	v_or_b32_e32 v144, s8, v135
	v_add_u32_e32 v151, v144, v134
	v_add_u32_e32 v144, v144, v132
	ds_read_b128 v[136:139], v151 offset:32768
	ds_read_b128 v[140:143], v151 offset:34816
	ds_read_b128 v[146:149], v151 offset:36864
	ds_read_b128 v[154:157], v151 offset:38912
	ds_read_b128 v[158:161], v144
	ds_read_b128 v[162:165], v144 offset:2048
	ds_read_b128 v[166:169], v144 offset:4096
	ds_read_b128 v[170:173], v144 offset:6144
	ds_read_b128 v[174:177], v144 offset:8192
	ds_read_b128 v[178:181], v144 offset:10240
	ds_read_b128 v[182:185], v144 offset:12288
	ds_read_b128 v[186:189], v144 offset:14336
	s_waitcnt lgkmcnt(0)
	v_mfma_f32_16x16x32_bf16 v[124:127], v[136:139], v[158:161], 0
	v_mfma_f32_16x16x32_bf16 v[120:123], v[140:143], v[158:161], 0
	v_mfma_f32_16x16x32_bf16 v[116:119], v[146:149], v[158:161], 0
	v_mfma_f32_16x16x32_bf16 v[112:115], v[154:157], v[158:161], 0
	v_mfma_f32_16x16x32_bf16 v[108:111], v[136:139], v[162:165], 0
	v_mfma_f32_16x16x32_bf16 v[104:107], v[140:143], v[162:165], 0
	v_mfma_f32_16x16x32_bf16 v[100:103], v[146:149], v[162:165], 0
	v_mfma_f32_16x16x32_bf16 v[96:99], v[154:157], v[162:165], 0
	v_mfma_f32_16x16x32_bf16 v[92:95], v[136:139], v[166:169], 0
	v_mfma_f32_16x16x32_bf16 v[84:87], v[140:143], v[166:169], 0
	v_mfma_f32_16x16x32_bf16 v[80:83], v[146:149], v[166:169], 0
	v_mfma_f32_16x16x32_bf16 v[76:79], v[154:157], v[166:169], 0
	v_mfma_f32_16x16x32_bf16 v[72:75], v[136:139], v[170:173], 0
	v_mfma_f32_16x16x32_bf16 v[68:71], v[140:143], v[170:173], 0
	v_mfma_f32_16x16x32_bf16 v[64:67], v[146:149], v[170:173], 0
	v_mfma_f32_16x16x32_bf16 v[60:63], v[154:157], v[170:173], 0
	v_or_b32_e32 v144, s8, v133
	v_add_u32_e32 v151, v144, v134
	v_add_u32_e32 v144, v144, v132
	ds_read_b128 v[158:161], v151 offset:32768
	ds_read_b128 v[162:165], v151 offset:34816
	ds_read_b128 v[166:169], v151 offset:36864
	ds_read_b128 v[170:173], v151 offset:38912
	ds_read_b128 v[206:209], v144
	ds_read_b128 v[216:219], v144 offset:2048
	ds_read_b128 v[220:223], v144 offset:4096
	ds_read_b128 v[224:227], v144 offset:6144
	v_mfma_f32_16x16x32_bf16 v[56:59], v[136:139], v[174:177], 0
	v_mfma_f32_16x16x32_bf16 v[52:55], v[140:143], v[174:177], 0
	v_mfma_f32_16x16x32_bf16 v[48:51], v[146:149], v[174:177], 0
	v_mfma_f32_16x16x32_bf16 v[44:47], v[154:157], v[174:177], 0
	v_mfma_f32_16x16x32_bf16 v[40:43], v[136:139], v[178:181], 0
	v_mfma_f32_16x16x32_bf16 v[36:39], v[140:143], v[178:181], 0
	v_mfma_f32_16x16x32_bf16 v[32:35], v[146:149], v[178:181], 0
	v_mfma_f32_16x16x32_bf16 v[28:31], v[154:157], v[178:181], 0
	v_mfma_f32_16x16x32_bf16 v[24:27], v[136:139], v[182:185], 0
	v_mfma_f32_16x16x32_bf16 v[20:23], v[140:143], v[182:185], 0
	v_mfma_f32_16x16x32_bf16 v[16:19], v[146:149], v[182:185], 0
	v_mfma_f32_16x16x32_bf16 v[12:15], v[154:157], v[182:185], 0
	v_mfma_f32_16x16x32_bf16 v[8:11], v[136:139], v[186:189], 0
	v_mfma_f32_16x16x32_bf16 v[4:7], v[140:143], v[186:189], 0
	v_mfma_f32_16x16x32_bf16 v[0:3], v[146:149], v[186:189], 0
	v_mfma_f32_16x16x32_bf16 v[88:91], v[154:157], v[186:189], 0
	ds_read_b128 v[136:139], v144 offset:8192
	ds_read_b128 v[140:143], v144 offset:10240
	ds_read_b128 v[146:149], v144 offset:12288
	ds_read_b128 v[154:157], v144 offset:14336
	s_waitcnt lgkmcnt(0)
	v_mfma_f32_16x16x32_bf16 v[124:127], v[158:161], v[206:209], v[124:127]
	v_mfma_f32_16x16x32_bf16 v[120:123], v[162:165], v[206:209], v[120:123]
	v_mfma_f32_16x16x32_bf16 v[116:119], v[166:169], v[206:209], v[116:119]
	v_mfma_f32_16x16x32_bf16 v[112:115], v[170:173], v[206:209], v[112:115]
	v_mfma_f32_16x16x32_bf16 v[108:111], v[158:161], v[216:219], v[108:111]
	v_mfma_f32_16x16x32_bf16 v[104:107], v[162:165], v[216:219], v[104:107]
	v_mfma_f32_16x16x32_bf16 v[100:103], v[166:169], v[216:219], v[100:103]
	v_mfma_f32_16x16x32_bf16 v[96:99], v[170:173], v[216:219], v[96:99]
	v_mfma_f32_16x16x32_bf16 v[92:95], v[158:161], v[220:223], v[92:95]
	v_mfma_f32_16x16x32_bf16 v[84:87], v[162:165], v[220:223], v[84:87]
	v_mfma_f32_16x16x32_bf16 v[80:83], v[166:169], v[220:223], v[80:83]
	v_mfma_f32_16x16x32_bf16 v[76:79], v[170:173], v[220:223], v[76:79]
	v_mfma_f32_16x16x32_bf16 v[72:75], v[158:161], v[224:227], v[72:75]
	v_mfma_f32_16x16x32_bf16 v[68:71], v[162:165], v[224:227], v[68:71]
	v_mfma_f32_16x16x32_bf16 v[64:67], v[166:169], v[224:227], v[64:67]
	v_mfma_f32_16x16x32_bf16 v[60:63], v[170:173], v[224:227], v[60:63]
	v_mfma_f32_16x16x32_bf16 v[56:59], v[158:161], v[136:139], v[56:59]
	s_add_u32 s6, s6, 0x80
	s_addc_u32 s7, s7, 0
	v_mfma_f32_16x16x32_bf16 v[52:55], v[162:165], v[136:139], v[52:55]
	s_cmpk_eq_i32 s6, 0x1580
	s_mov_b32 s8, s9
	s_waitcnt vmcnt(0)
	v_mfma_f32_16x16x32_bf16 v[48:51], v[166:169], v[136:139], v[48:51]
	s_barrier
	v_mfma_f32_16x16x32_bf16 v[44:47], v[170:173], v[136:139], v[44:47]
	v_mfma_f32_16x16x32_bf16 v[40:43], v[158:161], v[140:143], v[40:43]
	v_mfma_f32_16x16x32_bf16 v[36:39], v[162:165], v[140:143], v[36:39]
	v_mfma_f32_16x16x32_bf16 v[32:35], v[166:169], v[140:143], v[32:35]
	v_mfma_f32_16x16x32_bf16 v[28:31], v[170:173], v[140:143], v[28:31]
	v_mfma_f32_16x16x32_bf16 v[24:27], v[158:161], v[146:149], v[24:27]
	v_mfma_f32_16x16x32_bf16 v[20:23], v[162:165], v[146:149], v[20:23]
	v_mfma_f32_16x16x32_bf16 v[16:19], v[166:169], v[146:149], v[16:19]
	v_mfma_f32_16x16x32_bf16 v[12:15], v[170:173], v[146:149], v[12:15]
	v_mfma_f32_16x16x32_bf16 v[8:11], v[158:161], v[154:157], v[8:11]
	v_mfma_f32_16x16x32_bf16 v[4:7], v[162:165], v[154:157], v[4:7]
	v_mfma_f32_16x16x32_bf16 v[0:3], v[166:169], v[154:157], v[0:3]
	v_mfma_f32_16x16x32_bf16 v[88:91], v[170:173], v[154:157], v[88:91]
	s_cbranch_scc1 .Lkx_500
.LBB0_500:
	s_add_i32 s9, s8, 0x10000
	s_and_b32 s26, s9, 0x10000
	s_add_i32 s36, s3, s26
	v_lshl_add_u64 v[244:245], v[130:131], 0, s[6:7]
	s_mov_b64 s[26:27], 0x59e0080
	v_lshl_add_u64 v[246:247], v[244:245], 0, s[26:27]
	s_mov_b32 m0, s36
	s_mov_b64 s[26:27], 0x5a38080
	global_load_lds_dwordx4 v[246:247], off
	v_lshl_add_u64 v[246:247], v[244:245], 0, s[26:27]
	s_add_i32 m0, s36, 0x2000
	s_mov_b64 s[26:27], 0x5a90080
	global_load_lds_dwordx4 v[246:247], off
	v_lshl_add_u64 v[246:247], v[244:245], 0, s[26:27]
	s_add_i32 m0, s36, 0x4000
	s_mov_b64 s[26:27], 0x5ae8080
	global_load_lds_dwordx4 v[246:247], off
	v_lshl_add_u64 v[244:245], v[244:245], 0, s[26:27]
	s_add_i32 m0, s36, 0x6000
	s_mov_b64 s[26:27], 0x58080
	global_load_lds_dwordx4 v[244:245], off
	v_lshl_add_u64 v[244:245], v[128:129], 0, s[6:7]
	v_lshl_add_u64 v[246:247], v[244:245], 0, s[10:11]
	s_add_i32 m0, s36, 0x8000
	s_nop 0
	global_load_lds_dwordx4 v[246:247], off
	v_lshl_add_u64 v[246:247], v[244:245], 0, s[26:27]
	s_add_i32 m0, s36, 0xa000
	s_mov_b64 s[26:27], 0xb0080
	global_load_lds_dwordx4 v[246:247], off
	v_lshl_add_u64 v[246:247], v[244:245], 0, s[26:27]
	s_add_i32 m0, s36, 0xc000
	s_mov_b64 s[26:27], 0x108080
	global_load_lds_dwordx4 v[246:247], off
	v_lshl_add_u64 v[244:245], v[244:245], 0, s[26:27]
	s_add_i32 m0, s36, 0xe000
	s_nop 0
	global_load_lds_dwordx4 v[244:245], off
	s_and_b32 s8, s8, 0x10000
	v_or_b32_e32 v144, s8, v135
	v_add_u32_e32 v151, v144, v134
	v_add_u32_e32 v144, v144, v132
	ds_read_b128 v[136:139], v151 offset:32768
	ds_read_b128 v[140:143], v151 offset:34816
	ds_read_b128 v[146:149], v151 offset:36864
	ds_read_b128 v[154:157], v151 offset:38912
	ds_read_b128 v[158:161], v144
	ds_read_b128 v[162:165], v144 offset:2048
	ds_read_b128 v[166:169], v144 offset:4096
	ds_read_b128 v[170:173], v144 offset:6144
	ds_read_b128 v[174:177], v144 offset:8192
	ds_read_b128 v[178:181], v144 offset:10240
	ds_read_b128 v[182:185], v144 offset:12288
	ds_read_b128 v[186:189], v144 offset:14336
	s_waitcnt lgkmcnt(0)
	v_mfma_f32_16x16x32_bf16 v[124:127], v[136:139], v[158:161], v[124:127]
	v_mfma_f32_16x16x32_bf16 v[120:123], v[140:143], v[158:161], v[120:123]
	v_mfma_f32_16x16x32_bf16 v[116:119], v[146:149], v[158:161], v[116:119]
	v_mfma_f32_16x16x32_bf16 v[112:115], v[154:157], v[158:161], v[112:115]
	v_mfma_f32_16x16x32_bf16 v[108:111], v[136:139], v[162:165], v[108:111]
	v_mfma_f32_16x16x32_bf16 v[104:107], v[140:143], v[162:165], v[104:107]
	v_mfma_f32_16x16x32_bf16 v[100:103], v[146:149], v[162:165], v[100:103]
	v_mfma_f32_16x16x32_bf16 v[96:99], v[154:157], v[162:165], v[96:99]
	v_mfma_f32_16x16x32_bf16 v[92:95], v[136:139], v[166:169], v[92:95]
	v_mfma_f32_16x16x32_bf16 v[84:87], v[140:143], v[166:169], v[84:87]
	v_mfma_f32_16x16x32_bf16 v[80:83], v[146:149], v[166:169], v[80:83]
	v_mfma_f32_16x16x32_bf16 v[76:79], v[154:157], v[166:169], v[76:79]
	v_mfma_f32_16x16x32_bf16 v[72:75], v[136:139], v[170:173], v[72:75]
	v_mfma_f32_16x16x32_bf16 v[68:71], v[140:143], v[170:173], v[68:71]
	v_mfma_f32_16x16x32_bf16 v[64:67], v[146:149], v[170:173], v[64:67]
	v_mfma_f32_16x16x32_bf16 v[60:63], v[154:157], v[170:173], v[60:63]
	v_or_b32_e32 v144, s8, v133
	v_add_u32_e32 v151, v144, v134
	v_add_u32_e32 v144, v144, v132
	ds_read_b128 v[158:161], v151 offset:32768
	ds_read_b128 v[162:165], v151 offset:34816
	ds_read_b128 v[166:169], v151 offset:36864
	ds_read_b128 v[170:173], v151 offset:38912
	ds_read_b128 v[206:209], v144
	ds_read_b128 v[216:219], v144 offset:2048
	ds_read_b128 v[220:223], v144 offset:4096
	ds_read_b128 v[224:227], v144 offset:6144
	v_mfma_f32_16x16x32_bf16 v[56:59], v[136:139], v[174:177], v[56:59]
	v_mfma_f32_16x16x32_bf16 v[52:55], v[140:143], v[174:177], v[52:55]
	v_mfma_f32_16x16x32_bf16 v[48:51], v[146:149], v[174:177], v[48:51]
	v_mfma_f32_16x16x32_bf16 v[44:47], v[154:157], v[174:177], v[44:47]
	v_mfma_f32_16x16x32_bf16 v[40:43], v[136:139], v[178:181], v[40:43]
	v_mfma_f32_16x16x32_bf16 v[36:39], v[140:143], v[178:181], v[36:39]
	v_mfma_f32_16x16x32_bf16 v[32:35], v[146:149], v[178:181], v[32:35]
	v_mfma_f32_16x16x32_bf16 v[28:31], v[154:157], v[178:181], v[28:31]
	v_mfma_f32_16x16x32_bf16 v[24:27], v[136:139], v[182:185], v[24:27]
	v_mfma_f32_16x16x32_bf16 v[20:23], v[140:143], v[182:185], v[20:23]
	v_mfma_f32_16x16x32_bf16 v[16:19], v[146:149], v[182:185], v[16:19]
	v_mfma_f32_16x16x32_bf16 v[12:15], v[154:157], v[182:185], v[12:15]
	v_mfma_f32_16x16x32_bf16 v[8:11], v[136:139], v[186:189], v[8:11]
	v_mfma_f32_16x16x32_bf16 v[4:7], v[140:143], v[186:189], v[4:7]
	v_mfma_f32_16x16x32_bf16 v[0:3], v[146:149], v[186:189], v[0:3]
	v_mfma_f32_16x16x32_bf16 v[88:91], v[154:157], v[186:189], v[88:91]
	ds_read_b128 v[136:139], v144 offset:8192
	ds_read_b128 v[140:143], v144 offset:10240
	ds_read_b128 v[146:149], v144 offset:12288
	ds_read_b128 v[154:157], v144 offset:14336
	s_waitcnt lgkmcnt(0)
	v_mfma_f32_16x16x32_bf16 v[124:127], v[158:161], v[206:209], v[124:127]
	v_mfma_f32_16x16x32_bf16 v[120:123], v[162:165], v[206:209], v[120:123]
	v_mfma_f32_16x16x32_bf16 v[116:119], v[166:169], v[206:209], v[116:119]
	v_mfma_f32_16x16x32_bf16 v[112:115], v[170:173], v[206:209], v[112:115]
	v_mfma_f32_16x16x32_bf16 v[108:111], v[158:161], v[216:219], v[108:111]
	v_mfma_f32_16x16x32_bf16 v[104:107], v[162:165], v[216:219], v[104:107]
	v_mfma_f32_16x16x32_bf16 v[100:103], v[166:169], v[216:219], v[100:103]
	v_mfma_f32_16x16x32_bf16 v[96:99], v[170:173], v[216:219], v[96:99]
	v_mfma_f32_16x16x32_bf16 v[92:95], v[158:161], v[220:223], v[92:95]
	v_mfma_f32_16x16x32_bf16 v[84:87], v[162:165], v[220:223], v[84:87]
	v_mfma_f32_16x16x32_bf16 v[80:83], v[166:169], v[220:223], v[80:83]
	v_mfma_f32_16x16x32_bf16 v[76:79], v[170:173], v[220:223], v[76:79]
	v_mfma_f32_16x16x32_bf16 v[72:75], v[158:161], v[224:227], v[72:75]
	v_mfma_f32_16x16x32_bf16 v[68:71], v[162:165], v[224:227], v[68:71]
	v_mfma_f32_16x16x32_bf16 v[64:67], v[166:169], v[224:227], v[64:67]
	v_mfma_f32_16x16x32_bf16 v[60:63], v[170:173], v[224:227], v[60:63]
	v_mfma_f32_16x16x32_bf16 v[56:59], v[158:161], v[136:139], v[56:59]
	s_add_u32 s6, s6, 0x80
	s_addc_u32 s7, s7, 0
	v_mfma_f32_16x16x32_bf16 v[52:55], v[162:165], v[136:139], v[52:55]
	s_cmpk_eq_i32 s6, 0x1580
	s_mov_b32 s8, s9
	s_waitcnt vmcnt(0)
	v_mfma_f32_16x16x32_bf16 v[48:51], v[166:169], v[136:139], v[48:51]
	s_barrier
	v_mfma_f32_16x16x32_bf16 v[44:47], v[170:173], v[136:139], v[44:47]
	v_mfma_f32_16x16x32_bf16 v[40:43], v[158:161], v[140:143], v[40:43]
	v_mfma_f32_16x16x32_bf16 v[36:39], v[162:165], v[140:143], v[36:39]
	v_mfma_f32_16x16x32_bf16 v[32:35], v[166:169], v[140:143], v[32:35]
	v_mfma_f32_16x16x32_bf16 v[28:31], v[170:173], v[140:143], v[28:31]
	v_mfma_f32_16x16x32_bf16 v[24:27], v[158:161], v[146:149], v[24:27]
	v_mfma_f32_16x16x32_bf16 v[20:23], v[162:165], v[146:149], v[20:23]
	v_mfma_f32_16x16x32_bf16 v[16:19], v[166:169], v[146:149], v[16:19]
	v_mfma_f32_16x16x32_bf16 v[12:15], v[170:173], v[146:149], v[12:15]
	v_mfma_f32_16x16x32_bf16 v[8:11], v[158:161], v[154:157], v[8:11]
	v_mfma_f32_16x16x32_bf16 v[4:7], v[162:165], v[154:157], v[4:7]
	v_mfma_f32_16x16x32_bf16 v[0:3], v[166:169], v[154:157], v[0:3]
	v_mfma_f32_16x16x32_bf16 v[88:91], v[170:173], v[154:157], v[88:91]
	s_cbranch_scc0 .LBB0_500
	s_branch .Lkx_500
.Lkb_500:
	s_add_i32 s9, s8, 0x10000
	s_and_b32 s26, s9, 0x10000
	s_add_i32 s36, s3, s26
	s_and_b32 s8, s8, 0x10000
	v_or_b32_e32 v144, s8, v135
	v_add_u32_e32 v151, v144, v134
	v_add_u32_e32 v144, v144, v132
	ds_read_b128 v[136:139], v151 offset:32768
	ds_read_b128 v[140:143], v151 offset:34816
	ds_read_b128 v[146:149], v151 offset:36864
	ds_read_b128 v[154:157], v151 offset:38912
	ds_read_b128 v[158:161], v144
	ds_read_b128 v[162:165], v144 offset:2048
	ds_read_b128 v[166:169], v144 offset:4096
	ds_read_b128 v[170:173], v144 offset:6144
	ds_read_b128 v[174:177], v144 offset:8192
	ds_read_b128 v[178:181], v144 offset:10240
	ds_read_b128 v[182:185], v144 offset:12288
	ds_read_b128 v[186:189], v144 offset:14336
	s_waitcnt lgkmcnt(0)
	v_mfma_f32_16x16x32_bf16 v[124:127], v[136:139], v[158:161], 0
	v_mfma_f32_16x16x32_bf16 v[120:123], v[140:143], v[158:161], 0
	v_mfma_f32_16x16x32_bf16 v[116:119], v[146:149], v[158:161], 0
	v_mfma_f32_16x16x32_bf16 v[112:115], v[154:157], v[158:161], 0
	v_mfma_f32_16x16x32_bf16 v[108:111], v[136:139], v[162:165], 0
	v_mfma_f32_16x16x32_bf16 v[104:107], v[140:143], v[162:165], 0
	v_mfma_f32_16x16x32_bf16 v[100:103], v[146:149], v[162:165], 0
	v_mfma_f32_16x16x32_bf16 v[96:99], v[154:157], v[162:165], 0
	v_mfma_f32_16x16x32_bf16 v[92:95], v[136:139], v[166:169], 0
	v_mfma_f32_16x16x32_bf16 v[84:87], v[140:143], v[166:169], 0
	v_mfma_f32_16x16x32_bf16 v[80:83], v[146:149], v[166:169], 0
	v_mfma_f32_16x16x32_bf16 v[76:79], v[154:157], v[166:169], 0
	v_mfma_f32_16x16x32_bf16 v[72:75], v[136:139], v[170:173], 0
	v_mfma_f32_16x16x32_bf16 v[68:71], v[140:143], v[170:173], 0
	v_mfma_f32_16x16x32_bf16 v[64:67], v[146:149], v[170:173], 0
	v_mfma_f32_16x16x32_bf16 v[60:63], v[154:157], v[170:173], 0
	v_or_b32_e32 v144, s8, v133
	v_add_u32_e32 v151, v144, v134
	v_add_u32_e32 v144, v144, v132
	ds_read_b128 v[158:161], v151 offset:32768
	ds_read_b128 v[162:165], v151 offset:34816
	ds_read_b128 v[166:169], v151 offset:36864
	ds_read_b128 v[170:173], v151 offset:38912
	ds_read_b128 v[206:209], v144
	ds_read_b128 v[216:219], v144 offset:2048
	ds_read_b128 v[220:223], v144 offset:4096
	ds_read_b128 v[224:227], v144 offset:6144
	v_mfma_f32_16x16x32_bf16 v[56:59], v[136:139], v[174:177], 0
	v_mfma_f32_16x16x32_bf16 v[52:55], v[140:143], v[174:177], 0
	v_mfma_f32_16x16x32_bf16 v[48:51], v[146:149], v[174:177], 0
	v_mfma_f32_16x16x32_bf16 v[44:47], v[154:157], v[174:177], 0
	v_mfma_f32_16x16x32_bf16 v[40:43], v[136:139], v[178:181], 0
	v_mfma_f32_16x16x32_bf16 v[36:39], v[140:143], v[178:181], 0
	v_mfma_f32_16x16x32_bf16 v[32:35], v[146:149], v[178:181], 0
	v_mfma_f32_16x16x32_bf16 v[28:31], v[154:157], v[178:181], 0
	v_mfma_f32_16x16x32_bf16 v[24:27], v[136:139], v[182:185], 0
	v_mfma_f32_16x16x32_bf16 v[20:23], v[140:143], v[182:185], 0
	v_mfma_f32_16x16x32_bf16 v[16:19], v[146:149], v[182:185], 0
	v_mfma_f32_16x16x32_bf16 v[12:15], v[154:157], v[182:185], 0
	v_mfma_f32_16x16x32_bf16 v[8:11], v[136:139], v[186:189], 0
	v_mfma_f32_16x16x32_bf16 v[4:7], v[140:143], v[186:189], 0
	v_mfma_f32_16x16x32_bf16 v[0:3], v[146:149], v[186:189], 0
	v_mfma_f32_16x16x32_bf16 v[88:91], v[154:157], v[186:189], 0
	v_lshl_add_u64 v[244:245], v[130:131], 0, s[6:7]
	s_mov_b64 s[26:27], 0x59e0080
	v_lshl_add_u64 v[246:247], v[244:245], 0, s[26:27]
	s_mov_b32 m0, s36
	s_mov_b64 s[26:27], 0x5a38080
	global_load_lds_dwordx4 v[246:247], off
	v_lshl_add_u64 v[246:247], v[244:245], 0, s[26:27]
	s_add_i32 m0, s36, 0x2000
	s_mov_b64 s[26:27], 0x5a90080
	global_load_lds_dwordx4 v[246:247], off
	v_lshl_add_u64 v[246:247], v[244:245], 0, s[26:27]
	s_add_i32 m0, s36, 0x4000
	s_mov_b64 s[26:27], 0x5ae8080
	global_load_lds_dwordx4 v[246:247], off
	v_lshl_add_u64 v[244:245], v[244:245], 0, s[26:27]
	s_add_i32 m0, s36, 0x6000
	s_mov_b64 s[26:27], 0x58080
	global_load_lds_dwordx4 v[244:245], off
	v_lshl_add_u64 v[244:245], v[128:129], 0, s[6:7]
	v_lshl_add_u64 v[246:247], v[244:245], 0, s[10:11]
	s_add_i32 m0, s36, 0x8000
	s_nop 0
	global_load_lds_dwordx4 v[246:247], off
	v_lshl_add_u64 v[246:247], v[244:245], 0, s[26:27]
	s_add_i32 m0, s36, 0xa000
	s_mov_b64 s[26:27], 0xb0080
	global_load_lds_dwordx4 v[246:247], off
	v_lshl_add_u64 v[246:247], v[244:245], 0, s[26:27]
	s_add_i32 m0, s36, 0xc000
	s_mov_b64 s[26:27], 0x108080
	global_load_lds_dwordx4 v[246:247], off
	v_lshl_add_u64 v[244:245], v[244:245], 0, s[26:27]
	s_add_i32 m0, s36, 0xe000
	s_nop 0
	global_load_lds_dwordx4 v[244:245], off
	ds_read_b128 v[136:139], v144 offset:8192
	ds_read_b128 v[140:143], v144 offset:10240
	ds_read_b128 v[146:149], v144 offset:12288
	ds_read_b128 v[154:157], v144 offset:14336
	s_waitcnt lgkmcnt(0)
	v_mfma_f32_16x16x32_bf16 v[124:127], v[158:161], v[206:209], v[124:127]
	v_mfma_f32_16x16x32_bf16 v[120:123], v[162:165], v[206:209], v[120:123]
	v_mfma_f32_16x16x32_bf16 v[116:119], v[166:169], v[206:209], v[116:119]
	v_mfma_f32_16x16x32_bf16 v[112:115], v[170:173], v[206:209], v[112:115]
	v_mfma_f32_16x16x32_bf16 v[108:111], v[158:161], v[216:219], v[108:111]
	v_mfma_f32_16x16x32_bf16 v[104:107], v[162:165], v[216:219], v[104:107]
	v_mfma_f32_16x16x32_bf16 v[100:103], v[166:169], v[216:219], v[100:103]
	v_mfma_f32_16x16x32_bf16 v[96:99], v[170:173], v[216:219], v[96:99]
	v_mfma_f32_16x16x32_bf16 v[92:95], v[158:161], v[220:223], v[92:95]
	v_mfma_f32_16x16x32_bf16 v[84:87], v[162:165], v[220:223], v[84:87]
	v_mfma_f32_16x16x32_bf16 v[80:83], v[166:169], v[220:223], v[80:83]
	v_mfma_f32_16x16x32_bf16 v[76:79], v[170:173], v[220:223], v[76:79]
	v_mfma_f32_16x16x32_bf16 v[72:75], v[158:161], v[224:227], v[72:75]
	v_mfma_f32_16x16x32_bf16 v[68:71], v[162:165], v[224:227], v[68:71]
	v_mfma_f32_16x16x32_bf16 v[64:67], v[166:169], v[224:227], v[64:67]
	v_mfma_f32_16x16x32_bf16 v[60:63], v[170:173], v[224:227], v[60:63]
	v_mfma_f32_16x16x32_bf16 v[56:59], v[158:161], v[136:139], v[56:59]
	s_add_u32 s6, s6, 0x80
	s_addc_u32 s7, s7, 0
	v_mfma_f32_16x16x32_bf16 v[52:55], v[162:165], v[136:139], v[52:55]
	s_cmpk_eq_i32 s6, 0x1580
	s_mov_b32 s8, s9
	s_waitcnt vmcnt(0)
	v_mfma_f32_16x16x32_bf16 v[48:51], v[166:169], v[136:139], v[48:51]
	s_barrier
	v_mfma_f32_16x16x32_bf16 v[44:47], v[170:173], v[136:139], v[44:47]
	v_mfma_f32_16x16x32_bf16 v[40:43], v[158:161], v[140:143], v[40:43]
	v_mfma_f32_16x16x32_bf16 v[36:39], v[162:165], v[140:143], v[36:39]
	v_mfma_f32_16x16x32_bf16 v[32:35], v[166:169], v[140:143], v[32:35]
	v_mfma_f32_16x16x32_bf16 v[28:31], v[170:173], v[140:143], v[28:31]
	v_mfma_f32_16x16x32_bf16 v[24:27], v[158:161], v[146:149], v[24:27]
	v_mfma_f32_16x16x32_bf16 v[20:23], v[162:165], v[146:149], v[20:23]
	v_mfma_f32_16x16x32_bf16 v[16:19], v[166:169], v[146:149], v[16:19]
	v_mfma_f32_16x16x32_bf16 v[12:15], v[170:173], v[146:149], v[12:15]
	v_mfma_f32_16x16x32_bf16 v[8:11], v[158:161], v[154:157], v[8:11]
	v_mfma_f32_16x16x32_bf16 v[4:7], v[162:165], v[154:157], v[4:7]
	v_mfma_f32_16x16x32_bf16 v[0:3], v[166:169], v[154:157], v[0:3]
	v_mfma_f32_16x16x32_bf16 v[88:91], v[170:173], v[154:157], v[88:91]
	s_cbranch_scc1 .Lkx_500

.LBB0_669:
	v_lshlrev_b64 v[132:133], 10, v[0:1]
	v_and_b32_e32 v0, 15, v2
	v_and_b32_e32 v1, 3, v3
	v_lshrrev_b32_e32 v3, 1, v2
	s_mov_b32 s2, 0x1ffff80
	v_and_or_b32 v0, v3, s2, v0
	v_lshlrev_b32_e32 v134, 7, v0
	v_bfe_u32 v0, v2, 1, 3
	v_bitop3_b32 v0, v1, v0, 4 bitop3:0x36
	v_lshlrev_b32_e32 v135, 4, v0
	v_lshlrev_b32_e32 v0, 7, v2
	s_waitcnt vmcnt(0)
	v_bitop3_b32 v3, v3, v1, 7 bitop3:0x6c
	v_and_b32_e32 v136, 0x6780, v0
	v_lshlrev_b32_e32 v137, 4, v3
	s_mov_b64 s[34:35], 0
	s_mov_b32 s2, 0
	s_waitcnt vmcnt(0) lgkmcnt(0)
	s_barrier
	s_bitcmp1_b32 s0, 12
	s_cbranch_scc1 .Lkb_670
	s_add_i32 s3, s2, 0x10000
	s_and_b32 s23, s3, 0x10000
	s_add_i32 s23, s0, s23
	v_lshl_add_u64 v[244:245], v[128:129], 0, s[34:35]
	v_lshl_add_u64 v[246:247], v[244:245], 0, s[10:11]
	s_mov_b32 m0, s23
	s_nop 0
	global_load_lds_dwordx4 v[246:247], off
	v_lshl_add_u64 v[246:247], v[244:245], 0, s[4:5]
	s_add_i32 m0, s23, 0x2000
	s_nop 0
	global_load_lds_dwordx4 v[246:247], off
	v_lshl_add_u64 v[246:247], v[244:245], 0, s[92:93]
	s_add_i32 m0, s23, 0x4000
	v_lshl_add_u64 v[244:245], v[244:245], 0, s[94:95]
	global_load_lds_dwordx4 v[246:247], off
	s_add_i32 m0, s23, 0x6000
	s_nop 0
	global_load_lds_dwordx4 v[244:245], off
	v_lshl_add_u64 v[244:245], v[130:131], 0, s[34:35]
	v_lshl_add_u64 v[246:247], v[244:245], 0, s[10:11]
	s_add_i32 m0, s23, 0x8000
	s_nop 0
	global_load_lds_dwordx4 v[246:247], off
	v_lshl_add_u64 v[246:247], v[244:245], 0, s[4:5]
	s_add_i32 m0, s23, 0xa000
	s_nop 0
	global_load_lds_dwordx4 v[246:247], off
	v_lshl_add_u64 v[246:247], v[244:245], 0, s[92:93]
	s_add_i32 m0, s23, 0xc000
	v_lshl_add_u64 v[244:245], v[244:245], 0, s[94:95]
	global_load_lds_dwordx4 v[246:247], off
	s_add_i32 m0, s23, 0xe000
	s_nop 0
	global_load_lds_dwordx4 v[244:245], off
	s_and_b32 s2, s2, 0x10000
	v_or_b32_e32 v142, s2, v137
	v_add_u32_e32 v143, v142, v136
	v_add_u32_e32 v142, v142, v134
	ds_read_b128 v[138:141], v143 offset:32768
	ds_read_b128 v[146:149], v143 offset:34816
	ds_read_b128 v[154:157], v143 offset:36864
	ds_read_b128 v[158:161], v143 offset:38912
	ds_read_b128 v[162:165], v142
	ds_read_b128 v[166:169], v142 offset:2048
	ds_read_b128 v[170:173], v142 offset:4096
	ds_read_b128 v[174:177], v142 offset:6144
	ds_read_b128 v[178:181], v142 offset:8192
	ds_read_b128 v[182:185], v142 offset:10240
	ds_read_b128 v[186:189], v142 offset:12288
	ds_read_b128 v[206:209], v142 offset:14336
	s_waitcnt lgkmcnt(0)
	v_mfma_f32_16x16x32_bf16 v[116:119], v[138:141], v[162:165], 0
	v_mfma_f32_16x16x32_bf16 v[108:111], v[146:149], v[162:165], 0
	v_mfma_f32_16x16x32_bf16 v[100:103], v[154:157], v[162:165], 0
	v_mfma_f32_16x16x32_bf16 v[88:91], v[158:161], v[162:165], 0
	v_mfma_f32_16x16x32_bf16 v[76:79], v[138:141], v[166:169], 0
	v_mfma_f32_16x16x32_bf16 v[68:71], v[146:149], v[166:169], 0
	v_mfma_f32_16x16x32_bf16 v[56:59], v[154:157], v[166:169], 0
	v_mfma_f32_16x16x32_bf16 v[44:47], v[158:161], v[166:169], 0
	v_mfma_f32_16x16x32_bf16 v[36:39], v[138:141], v[170:173], 0
	v_mfma_f32_16x16x32_bf16 v[32:35], v[146:149], v[170:173], 0
	v_mfma_f32_16x16x32_bf16 v[28:31], v[154:157], v[170:173], 0
	v_mfma_f32_16x16x32_bf16 v[24:27], v[158:161], v[170:173], 0
	v_mfma_f32_16x16x32_bf16 v[20:23], v[138:141], v[174:177], 0
	v_mfma_f32_16x16x32_bf16 v[16:19], v[146:149], v[174:177], 0
	v_mfma_f32_16x16x32_bf16 v[12:15], v[154:157], v[174:177], 0
	v_mfma_f32_16x16x32_bf16 v[8:11], v[158:161], v[174:177], 0
	v_or_b32_e32 v142, s2, v135
	v_add_u32_e32 v143, v142, v136
	v_add_u32_e32 v142, v142, v134
	ds_read_b128 v[162:165], v143 offset:32768
	ds_read_b128 v[166:169], v143 offset:34816
	ds_read_b128 v[170:173], v143 offset:36864
	ds_read_b128 v[174:177], v143 offset:38912
	ds_read_b128 v[216:219], v142
	ds_read_b128 v[220:223], v142 offset:2048
	ds_read_b128 v[224:227], v142 offset:4096
	ds_read_b128 v[228:231], v142 offset:6144
	v_mfma_f32_16x16x32_bf16 v[4:7], v[138:141], v[178:181], 0
	v_mfma_f32_16x16x32_bf16 v[0:3], v[146:149], v[178:181], 0
	v_mfma_f32_16x16x32_bf16 v[40:43], v[154:157], v[178:181], 0
	v_mfma_f32_16x16x32_bf16 v[48:51], v[158:161], v[178:181], 0
	v_mfma_f32_16x16x32_bf16 v[52:55], v[138:141], v[182:185], 0
	v_mfma_f32_16x16x32_bf16 v[60:63], v[146:149], v[182:185], 0
	v_mfma_f32_16x16x32_bf16 v[64:67], v[154:157], v[182:185], 0
	v_mfma_f32_16x16x32_bf16 v[72:75], v[158:161], v[182:185], 0
	v_mfma_f32_16x16x32_bf16 v[80:83], v[138:141], v[186:189], 0
	v_mfma_f32_16x16x32_bf16 v[84:87], v[146:149], v[186:189], 0
	v_mfma_f32_16x16x32_bf16 v[92:95], v[154:157], v[186:189], 0
	v_mfma_f32_16x16x32_bf16 v[96:99], v[158:161], v[186:189], 0
	v_mfma_f32_16x16x32_bf16 v[104:107], v[138:141], v[206:209], 0
	v_mfma_f32_16x16x32_bf16 v[112:115], v[146:149], v[206:209], 0
	v_mfma_f32_16x16x32_bf16 v[120:123], v[154:157], v[206:209], 0
	v_mfma_f32_16x16x32_bf16 v[124:127], v[158:161], v[206:209], 0
	ds_read_b128 v[138:141], v142 offset:8192
	ds_read_b128 v[146:149], v142 offset:10240
	ds_read_b128 v[154:157], v142 offset:12288
	ds_read_b128 v[158:161], v142 offset:14336
	s_waitcnt lgkmcnt(0)
	v_mfma_f32_16x16x32_bf16 v[116:119], v[162:165], v[216:219], v[116:119]
	v_mfma_f32_16x16x32_bf16 v[108:111], v[166:169], v[216:219], v[108:111]
	v_mfma_f32_16x16x32_bf16 v[100:103], v[170:173], v[216:219], v[100:103]
	v_mfma_f32_16x16x32_bf16 v[88:91], v[174:177], v[216:219], v[88:91]
	v_mfma_f32_16x16x32_bf16 v[76:79], v[162:165], v[220:223], v[76:79]
	v_mfma_f32_16x16x32_bf16 v[68:71], v[166:169], v[220:223], v[68:71]
	v_mfma_f32_16x16x32_bf16 v[56:59], v[170:173], v[220:223], v[56:59]
	v_mfma_f32_16x16x32_bf16 v[44:47], v[174:177], v[220:223], v[44:47]
	v_mfma_f32_16x16x32_bf16 v[36:39], v[162:165], v[224:227], v[36:39]
	v_mfma_f32_16x16x32_bf16 v[32:35], v[166:169], v[224:227], v[32:35]
	v_mfma_f32_16x16x32_bf16 v[28:31], v[170:173], v[224:227], v[28:31]
	v_mfma_f32_16x16x32_bf16 v[24:27], v[174:177], v[224:227], v[24:27]
	v_mfma_f32_16x16x32_bf16 v[20:23], v[162:165], v[228:231], v[20:23]
	v_mfma_f32_16x16x32_bf16 v[16:19], v[166:169], v[228:231], v[16:19]
	v_mfma_f32_16x16x32_bf16 v[12:15], v[170:173], v[228:231], v[12:15]
	v_mfma_f32_16x16x32_bf16 v[8:11], v[174:177], v[228:231], v[8:11]
	v_mfma_f32_16x16x32_bf16 v[4:7], v[162:165], v[138:141], v[4:7]
	s_add_u32 s34, s34, 0x80
	s_addc_u32 s35, s35, 0
	v_mfma_f32_16x16x32_bf16 v[0:3], v[166:169], v[138:141], v[0:3]
	s_cmpk_eq_i32 s34, 0x780
	s_mov_b32 s2, s3
	s_waitcnt vmcnt(0)
	v_mfma_f32_16x16x32_bf16 v[40:43], v[170:173], v[138:141], v[40:43]
	s_barrier
	v_mfma_f32_16x16x32_bf16 v[48:51], v[174:177], v[138:141], v[48:51]
	v_mfma_f32_16x16x32_bf16 v[52:55], v[162:165], v[146:149], v[52:55]
	v_mfma_f32_16x16x32_bf16 v[60:63], v[166:169], v[146:149], v[60:63]
	v_mfma_f32_16x16x32_bf16 v[64:67], v[170:173], v[146:149], v[64:67]
	v_mfma_f32_16x16x32_bf16 v[72:75], v[174:177], v[146:149], v[72:75]
	v_mfma_f32_16x16x32_bf16 v[80:83], v[162:165], v[154:157], v[80:83]
	v_mfma_f32_16x16x32_bf16 v[84:87], v[166:169], v[154:157], v[84:87]
	v_mfma_f32_16x16x32_bf16 v[92:95], v[170:173], v[154:157], v[92:95]
	v_mfma_f32_16x16x32_bf16 v[96:99], v[174:177], v[154:157], v[96:99]
	v_mfma_f32_16x16x32_bf16 v[104:107], v[162:165], v[158:161], v[104:107]
	v_mfma_f32_16x16x32_bf16 v[112:115], v[166:169], v[158:161], v[112:115]
	v_mfma_f32_16x16x32_bf16 v[120:123], v[170:173], v[158:161], v[120:123]
	v_mfma_f32_16x16x32_bf16 v[124:127], v[174:177], v[158:161], v[124:127]
	s_cbranch_scc1 .Lkx_670
.LBB0_670:
	s_add_i32 s3, s2, 0x10000
	s_and_b32 s23, s3, 0x10000
	s_add_i32 s23, s0, s23
	v_lshl_add_u64 v[244:245], v[128:129], 0, s[34:35]
	v_lshl_add_u64 v[246:247], v[244:245], 0, s[10:11]
	s_mov_b32 m0, s23
	s_nop 0
	global_load_lds_dwordx4 v[246:247], off
	v_lshl_add_u64 v[246:247], v[244:245], 0, s[4:5]
	s_add_i32 m0, s23, 0x2000
	s_nop 0
	global_load_lds_dwordx4 v[246:247], off
	v_lshl_add_u64 v[246:247], v[244:245], 0, s[92:93]
	s_add_i32 m0, s23, 0x4000
	v_lshl_add_u64 v[244:245], v[244:245], 0, s[94:95]
	global_load_lds_dwordx4 v[246:247], off
	s_add_i32 m0, s23, 0x6000
	s_nop 0
	global_load_lds_dwordx4 v[244:245], off
	v_lshl_add_u64 v[244:245], v[130:131], 0, s[34:35]
	v_lshl_add_u64 v[246:247], v[244:245], 0, s[10:11]
	s_add_i32 m0, s23, 0x8000
	s_nop 0
	global_load_lds_dwordx4 v[246:247], off
	v_lshl_add_u64 v[246:247], v[244:245], 0, s[4:5]
	s_add_i32 m0, s23, 0xa000
	s_nop 0
	global_load_lds_dwordx4 v[246:247], off
	v_lshl_add_u64 v[246:247], v[244:245], 0, s[92:93]
	s_add_i32 m0, s23, 0xc000
	v_lshl_add_u64 v[244:245], v[244:245], 0, s[94:95]
	global_load_lds_dwordx4 v[246:247], off
	s_add_i32 m0, s23, 0xe000
	s_nop 0
	global_load_lds_dwordx4 v[244:245], off
	s_and_b32 s2, s2, 0x10000
	v_or_b32_e32 v142, s2, v137
	v_add_u32_e32 v143, v142, v136
	v_add_u32_e32 v142, v142, v134
	ds_read_b128 v[138:141], v143 offset:32768
	ds_read_b128 v[146:149], v143 offset:34816
	ds_read_b128 v[154:157], v143 offset:36864
	ds_read_b128 v[158:161], v143 offset:38912
	ds_read_b128 v[162:165], v142
	ds_read_b128 v[166:169], v142 offset:2048
	ds_read_b128 v[170:173], v142 offset:4096
	ds_read_b128 v[174:177], v142 offset:6144
	ds_read_b128 v[178:181], v142 offset:8192
	ds_read_b128 v[182:185], v142 offset:10240
	ds_read_b128 v[186:189], v142 offset:12288
	ds_read_b128 v[206:209], v142 offset:14336
	s_waitcnt lgkmcnt(0)
	v_mfma_f32_16x16x32_bf16 v[116:119], v[138:141], v[162:165], v[116:119]
	v_mfma_f32_16x16x32_bf16 v[108:111], v[146:149], v[162:165], v[108:111]
	v_mfma_f32_16x16x32_bf16 v[100:103], v[154:157], v[162:165], v[100:103]
	v_mfma_f32_16x16x32_bf16 v[88:91], v[158:161], v[162:165], v[88:91]
	v_mfma_f32_16x16x32_bf16 v[76:79], v[138:141], v[166:169], v[76:79]
	v_mfma_f32_16x16x32_bf16 v[68:71], v[146:149], v[166:169], v[68:71]
	v_mfma_f32_16x16x32_bf16 v[56:59], v[154:157], v[166:169], v[56:59]
	v_mfma_f32_16x16x32_bf16 v[44:47], v[158:161], v[166:169], v[44:47]
	v_mfma_f32_16x16x32_bf16 v[36:39], v[138:141], v[170:173], v[36:39]
	v_mfma_f32_16x16x32_bf16 v[32:35], v[146:149], v[170:173], v[32:35]
	v_mfma_f32_16x16x32_bf16 v[28:31], v[154:157], v[170:173], v[28:31]
	v_mfma_f32_16x16x32_bf16 v[24:27], v[158:161], v[170:173], v[24:27]
	v_mfma_f32_16x16x32_bf16 v[20:23], v[138:141], v[174:177], v[20:23]
	v_mfma_f32_16x16x32_bf16 v[16:19], v[146:149], v[174:177], v[16:19]
	v_mfma_f32_16x16x32_bf16 v[12:15], v[154:157], v[174:177], v[12:15]
	v_mfma_f32_16x16x32_bf16 v[8:11], v[158:161], v[174:177], v[8:11]
	v_or_b32_e32 v142, s2, v135
	v_add_u32_e32 v143, v142, v136
	v_add_u32_e32 v142, v142, v134
	ds_read_b128 v[162:165], v143 offset:32768
	ds_read_b128 v[166:169], v143 offset:34816
	ds_read_b128 v[170:173], v143 offset:36864
	ds_read_b128 v[174:177], v143 offset:38912
	ds_read_b128 v[216:219], v142
	ds_read_b128 v[220:223], v142 offset:2048
	ds_read_b128 v[224:227], v142 offset:4096
	ds_read_b128 v[228:231], v142 offset:6144
	v_mfma_f32_16x16x32_bf16 v[4:7], v[138:141], v[178:181], v[4:7]
	v_mfma_f32_16x16x32_bf16 v[0:3], v[146:149], v[178:181], v[0:3]
	v_mfma_f32_16x16x32_bf16 v[40:43], v[154:157], v[178:181], v[40:43]
	v_mfma_f32_16x16x32_bf16 v[48:51], v[158:161], v[178:181], v[48:51]
	v_mfma_f32_16x16x32_bf16 v[52:55], v[138:141], v[182:185], v[52:55]
	v_mfma_f32_16x16x32_bf16 v[60:63], v[146:149], v[182:185], v[60:63]
	v_mfma_f32_16x16x32_bf16 v[64:67], v[154:157], v[182:185], v[64:67]
	v_mfma_f32_16x16x32_bf16 v[72:75], v[158:161], v[182:185], v[72:75]
	v_mfma_f32_16x16x32_bf16 v[80:83], v[138:141], v[186:189], v[80:83]
	v_mfma_f32_16x16x32_bf16 v[84:87], v[146:149], v[186:189], v[84:87]
	v_mfma_f32_16x16x32_bf16 v[92:95], v[154:157], v[186:189], v[92:95]
	v_mfma_f32_16x16x32_bf16 v[96:99], v[158:161], v[186:189], v[96:99]
	v_mfma_f32_16x16x32_bf16 v[104:107], v[138:141], v[206:209], v[104:107]
	v_mfma_f32_16x16x32_bf16 v[112:115], v[146:149], v[206:209], v[112:115]
	v_mfma_f32_16x16x32_bf16 v[120:123], v[154:157], v[206:209], v[120:123]
	v_mfma_f32_16x16x32_bf16 v[124:127], v[158:161], v[206:209], v[124:127]
	ds_read_b128 v[138:141], v142 offset:8192
	ds_read_b128 v[146:149], v142 offset:10240
	ds_read_b128 v[154:157], v142 offset:12288
	ds_read_b128 v[158:161], v142 offset:14336
	s_waitcnt lgkmcnt(0)
	v_mfma_f32_16x16x32_bf16 v[116:119], v[162:165], v[216:219], v[116:119]
	v_mfma_f32_16x16x32_bf16 v[108:111], v[166:169], v[216:219], v[108:111]
	v_mfma_f32_16x16x32_bf16 v[100:103], v[170:173], v[216:219], v[100:103]
	v_mfma_f32_16x16x32_bf16 v[88:91], v[174:177], v[216:219], v[88:91]
	v_mfma_f32_16x16x32_bf16 v[76:79], v[162:165], v[220:223], v[76:79]
	v_mfma_f32_16x16x32_bf16 v[68:71], v[166:169], v[220:223], v[68:71]
	v_mfma_f32_16x16x32_bf16 v[56:59], v[170:173], v[220:223], v[56:59]
	v_mfma_f32_16x16x32_bf16 v[44:47], v[174:177], v[220:223], v[44:47]
	v_mfma_f32_16x16x32_bf16 v[36:39], v[162:165], v[224:227], v[36:39]
	v_mfma_f32_16x16x32_bf16 v[32:35], v[166:169], v[224:227], v[32:35]
	v_mfma_f32_16x16x32_bf16 v[28:31], v[170:173], v[224:227], v[28:31]
	v_mfma_f32_16x16x32_bf16 v[24:27], v[174:177], v[224:227], v[24:27]
	v_mfma_f32_16x16x32_bf16 v[20:23], v[162:165], v[228:231], v[20:23]
	v_mfma_f32_16x16x32_bf16 v[16:19], v[166:169], v[228:231], v[16:19]
	v_mfma_f32_16x16x32_bf16 v[12:15], v[170:173], v[228:231], v[12:15]
	v_mfma_f32_16x16x32_bf16 v[8:11], v[174:177], v[228:231], v[8:11]
	v_mfma_f32_16x16x32_bf16 v[4:7], v[162:165], v[138:141], v[4:7]
	s_add_u32 s34, s34, 0x80
	s_addc_u32 s35, s35, 0
	v_mfma_f32_16x16x32_bf16 v[0:3], v[166:169], v[138:141], v[0:3]
	s_cmpk_eq_i32 s34, 0x780
	s_mov_b32 s2, s3
	s_waitcnt vmcnt(0)
	v_mfma_f32_16x16x32_bf16 v[40:43], v[170:173], v[138:141], v[40:43]
	s_barrier
	v_mfma_f32_16x16x32_bf16 v[48:51], v[174:177], v[138:141], v[48:51]
	v_mfma_f32_16x16x32_bf16 v[52:55], v[162:165], v[146:149], v[52:55]
	v_mfma_f32_16x16x32_bf16 v[60:63], v[166:169], v[146:149], v[60:63]
	v_mfma_f32_16x16x32_bf16 v[64:67], v[170:173], v[146:149], v[64:67]
	v_mfma_f32_16x16x32_bf16 v[72:75], v[174:177], v[146:149], v[72:75]
	v_mfma_f32_16x16x32_bf16 v[80:83], v[162:165], v[154:157], v[80:83]
	v_mfma_f32_16x16x32_bf16 v[84:87], v[166:169], v[154:157], v[84:87]
	v_mfma_f32_16x16x32_bf16 v[92:95], v[170:173], v[154:157], v[92:95]
	v_mfma_f32_16x16x32_bf16 v[96:99], v[174:177], v[154:157], v[96:99]
	v_mfma_f32_16x16x32_bf16 v[104:107], v[162:165], v[158:161], v[104:107]
	v_mfma_f32_16x16x32_bf16 v[112:115], v[166:169], v[158:161], v[112:115]
	v_mfma_f32_16x16x32_bf16 v[120:123], v[170:173], v[158:161], v[120:123]
	v_mfma_f32_16x16x32_bf16 v[124:127], v[174:177], v[158:161], v[124:127]
	s_cbranch_scc0 .LBB0_670
	s_branch .Lkx_670
.Lkb_670:
	s_add_i32 s3, s2, 0x10000
	s_and_b32 s23, s3, 0x10000
	s_add_i32 s23, s0, s23
	s_and_b32 s2, s2, 0x10000
	v_or_b32_e32 v142, s2, v137
	v_add_u32_e32 v143, v142, v136
	v_add_u32_e32 v142, v142, v134
	ds_read_b128 v[138:141], v143 offset:32768
	ds_read_b128 v[146:149], v143 offset:34816
	ds_read_b128 v[154:157], v143 offset:36864
	ds_read_b128 v[158:161], v143 offset:38912
	ds_read_b128 v[162:165], v142
	ds_read_b128 v[166:169], v142 offset:2048
	ds_read_b128 v[170:173], v142 offset:4096
	ds_read_b128 v[174:177], v142 offset:6144
	ds_read_b128 v[178:181], v142 offset:8192
	ds_read_b128 v[182:185], v142 offset:10240
	ds_read_b128 v[186:189], v142 offset:12288
	ds_read_b128 v[206:209], v142 offset:14336
	s_waitcnt lgkmcnt(0)
	v_mfma_f32_16x16x32_bf16 v[116:119], v[138:141], v[162:165], 0
	v_mfma_f32_16x16x32_bf16 v[108:111], v[146:149], v[162:165], 0
	v_mfma_f32_16x16x32_bf16 v[100:103], v[154:157], v[162:165], 0
	v_mfma_f32_16x16x32_bf16 v[88:91], v[158:161], v[162:165], 0
	v_mfma_f32_16x16x32_bf16 v[76:79], v[138:141], v[166:169], 0
	v_mfma_f32_16x16x32_bf16 v[68:71], v[146:149], v[166:169], 0
	v_mfma_f32_16x16x32_bf16 v[56:59], v[154:157], v[166:169], 0
	v_mfma_f32_16x16x32_bf16 v[44:47], v[158:161], v[166:169], 0
	v_mfma_f32_16x16x32_bf16 v[36:39], v[138:141], v[170:173], 0
	v_mfma_f32_16x16x32_bf16 v[32:35], v[146:149], v[170:173], 0
	v_mfma_f32_16x16x32_bf16 v[28:31], v[154:157], v[170:173], 0
	v_mfma_f32_16x16x32_bf16 v[24:27], v[158:161], v[170:173], 0
	v_mfma_f32_16x16x32_bf16 v[20:23], v[138:141], v[174:177], 0
	v_mfma_f32_16x16x32_bf16 v[16:19], v[146:149], v[174:177], 0
	v_mfma_f32_16x16x32_bf16 v[12:15], v[154:157], v[174:177], 0
	v_mfma_f32_16x16x32_bf16 v[8:11], v[158:161], v[174:177], 0
	v_or_b32_e32 v142, s2, v135
	v_add_u32_e32 v143, v142, v136
	v_add_u32_e32 v142, v142, v134
	ds_read_b128 v[162:165], v143 offset:32768
	ds_read_b128 v[166:169], v143 offset:34816
	ds_read_b128 v[170:173], v143 offset:36864
	ds_read_b128 v[174:177], v143 offset:38912
	ds_read_b128 v[216:219], v142
	ds_read_b128 v[220:223], v142 offset:2048
	ds_read_b128 v[224:227], v142 offset:4096
	ds_read_b128 v[228:231], v142 offset:6144
	v_mfma_f32_16x16x32_bf16 v[4:7], v[138:141], v[178:181], 0
	v_mfma_f32_16x16x32_bf16 v[0:3], v[146:149], v[178:181], 0
	v_mfma_f32_16x16x32_bf16 v[40:43], v[154:157], v[178:181], 0
	v_mfma_f32_16x16x32_bf16 v[48:51], v[158:161], v[178:181], 0
	v_mfma_f32_16x16x32_bf16 v[52:55], v[138:141], v[182:185], 0
	v_mfma_f32_16x16x32_bf16 v[60:63], v[146:149], v[182:185], 0
	v_mfma_f32_16x16x32_bf16 v[64:67], v[154:157], v[182:185], 0
	v_mfma_f32_16x16x32_bf16 v[72:75], v[158:161], v[182:185], 0
	v_mfma_f32_16x16x32_bf16 v[80:83], v[138:141], v[186:189], 0
	v_mfma_f32_16x16x32_bf16 v[84:87], v[146:149], v[186:189], 0
	v_mfma_f32_16x16x32_bf16 v[92:95], v[154:157], v[186:189], 0
	v_mfma_f32_16x16x32_bf16 v[96:99], v[158:161], v[186:189], 0
	v_mfma_f32_16x16x32_bf16 v[104:107], v[138:141], v[206:209], 0
	v_mfma_f32_16x16x32_bf16 v[112:115], v[146:149], v[206:209], 0
	v_mfma_f32_16x16x32_bf16 v[120:123], v[154:157], v[206:209], 0
	v_mfma_f32_16x16x32_bf16 v[124:127], v[158:161], v[206:209], 0
	v_lshl_add_u64 v[244:245], v[128:129], 0, s[34:35]
	v_lshl_add_u64 v[246:247], v[244:245], 0, s[10:11]
	s_mov_b32 m0, s23
	s_nop 0
	global_load_lds_dwordx4 v[246:247], off
	v_lshl_add_u64 v[246:247], v[244:245], 0, s[4:5]
	s_add_i32 m0, s23, 0x2000
	s_nop 0
	global_load_lds_dwordx4 v[246:247], off
	v_lshl_add_u64 v[246:247], v[244:245], 0, s[92:93]
	s_add_i32 m0, s23, 0x4000
	v_lshl_add_u64 v[244:245], v[244:245], 0, s[94:95]
	global_load_lds_dwordx4 v[246:247], off
	s_add_i32 m0, s23, 0x6000
	s_nop 0
	global_load_lds_dwordx4 v[244:245], off
	v_lshl_add_u64 v[244:245], v[130:131], 0, s[34:35]
	v_lshl_add_u64 v[246:247], v[244:245], 0, s[10:11]
	s_add_i32 m0, s23, 0x8000
	s_nop 0
	global_load_lds_dwordx4 v[246:247], off
	v_lshl_add_u64 v[246:247], v[244:245], 0, s[4:5]
	s_add_i32 m0, s23, 0xa000
	s_nop 0
	global_load_lds_dwordx4 v[246:247], off
	v_lshl_add_u64 v[246:247], v[244:245], 0, s[92:93]
	s_add_i32 m0, s23, 0xc000
	v_lshl_add_u64 v[244:245], v[244:245], 0, s[94:95]
	global_load_lds_dwordx4 v[246:247], off
	s_add_i32 m0, s23, 0xe000
	s_nop 0
	global_load_lds_dwordx4 v[244:245], off
	ds_read_b128 v[138:141], v142 offset:8192
	ds_read_b128 v[146:149], v142 offset:10240
	ds_read_b128 v[154:157], v142 offset:12288
	ds_read_b128 v[158:161], v142 offset:14336
	s_waitcnt lgkmcnt(0)
	v_mfma_f32_16x16x32_bf16 v[116:119], v[162:165], v[216:219], v[116:119]
	v_mfma_f32_16x16x32_bf16 v[108:111], v[166:169], v[216:219], v[108:111]
	v_mfma_f32_16x16x32_bf16 v[100:103], v[170:173], v[216:219], v[100:103]
	v_mfma_f32_16x16x32_bf16 v[88:91], v[174:177], v[216:219], v[88:91]
	v_mfma_f32_16x16x32_bf16 v[76:79], v[162:165], v[220:223], v[76:79]
	v_mfma_f32_16x16x32_bf16 v[68:71], v[166:169], v[220:223], v[68:71]
	v_mfma_f32_16x16x32_bf16 v[56:59], v[170:173], v[220:223], v[56:59]
	v_mfma_f32_16x16x32_bf16 v[44:47], v[174:177], v[220:223], v[44:47]
	v_mfma_f32_16x16x32_bf16 v[36:39], v[162:165], v[224:227], v[36:39]
	v_mfma_f32_16x16x32_bf16 v[32:35], v[166:169], v[224:227], v[32:35]
	v_mfma_f32_16x16x32_bf16 v[28:31], v[170:173], v[224:227], v[28:31]
	v_mfma_f32_16x16x32_bf16 v[24:27], v[174:177], v[224:227], v[24:27]
	v_mfma_f32_16x16x32_bf16 v[20:23], v[162:165], v[228:231], v[20:23]
	v_mfma_f32_16x16x32_bf16 v[16:19], v[166:169], v[228:231], v[16:19]
	v_mfma_f32_16x16x32_bf16 v[12:15], v[170:173], v[228:231], v[12:15]
	v_mfma_f32_16x16x32_bf16 v[8:11], v[174:177], v[228:231], v[8:11]
	v_mfma_f32_16x16x32_bf16 v[4:7], v[162:165], v[138:141], v[4:7]
	s_add_u32 s34, s34, 0x80
	s_addc_u32 s35, s35, 0
	v_mfma_f32_16x16x32_bf16 v[0:3], v[166:169], v[138:141], v[0:3]
	s_cmpk_eq_i32 s34, 0x780
	s_mov_b32 s2, s3
	s_waitcnt vmcnt(0)
	v_mfma_f32_16x16x32_bf16 v[40:43], v[170:173], v[138:141], v[40:43]
	s_barrier
	v_mfma_f32_16x16x32_bf16 v[48:51], v[174:177], v[138:141], v[48:51]
	v_mfma_f32_16x16x32_bf16 v[52:55], v[162:165], v[146:149], v[52:55]
	v_mfma_f32_16x16x32_bf16 v[60:63], v[166:169], v[146:149], v[60:63]
	v_mfma_f32_16x16x32_bf16 v[64:67], v[170:173], v[146:149], v[64:67]
	v_mfma_f32_16x16x32_bf16 v[72:75], v[174:177], v[146:149], v[72:75]
	v_mfma_f32_16x16x32_bf16 v[80:83], v[162:165], v[154:157], v[80:83]
	v_mfma_f32_16x16x32_bf16 v[84:87], v[166:169], v[154:157], v[84:87]
	v_mfma_f32_16x16x32_bf16 v[92:95], v[170:173], v[154:157], v[92:95]
	v_mfma_f32_16x16x32_bf16 v[96:99], v[174:177], v[154:157], v[96:99]
	v_mfma_f32_16x16x32_bf16 v[104:107], v[162:165], v[158:161], v[104:107]
	v_mfma_f32_16x16x32_bf16 v[112:115], v[166:169], v[158:161], v[112:115]
	v_mfma_f32_16x16x32_bf16 v[120:123], v[170:173], v[158:161], v[120:123]
	v_mfma_f32_16x16x32_bf16 v[124:127], v[174:177], v[158:161], v[124:127]
	s_cbranch_scc1 .Lkx_670
